# conv phase: non-temporal (nt) hint on the read-once f32 weight tile loads
# baseline (speedup 1.0000x reference)
; DI void tr_item(const float* W, int N, const float* scale, bf16_t* WT, int ldk, int koff, int gu, int which, float* scr, int item, int lane) {
;     const int nblk = N >> 6, kb = item / nblk, nb = item - kb * nblk, k0 = 64 * kb, n0 = 64 * nb;
;     const int lr = lane >> 4, lc = (lane & 15) * 4;
;     f32x4 v[16];
; #pragma unroll
;     for (int i = 0; i < 16; ++i) v[i] = *(const f32x4*)(W + (size_t)(k0 + 4 * i + lr) * N + n0 + lc);
; #pragma unroll
;     for (int i = 0; i < 16; ++i) { const int kk = 4 * i + lr; const float sc = scale ? scale[k0 + kk] : 1.f; float* d = scr + kk * 65 + lc;
;         d[0] = v[i].x * sc; d[1] = v[i].y * sc; d[2] = v[i].z * sc; d[3] = v[i].w * sc; }
; DI void conv_phase(PP P, int l, unsigned char* lds, int G, int cid) {
;     ...
;         tr_item(P->in[27] + (size_t)l * DFF * DM, DM, nullptr, (bf16_t*)(ws + WS_WDN), DFF, 0, 0, 0, scr, r, lane);
.LBB0_385:
	v_add_u32_e32 v0, 0x2f00, v113
	s_movk_i32 s4, 0xfff
	v_cmp_lt_i32_e32 vcc, s4, v0
	s_and_saveexec_b64 s[4:5], vcc
	s_xor_b64 s[68:69], exec, s[4:5]
	s_cbranch_execz .LBB0_459
	s_movk_i32 s4, 0x10ff
	v_cmp_lt_u32_e32 vcc, s4, v0
	s_and_saveexec_b64 s[4:5], vcc
	s_xor_b64 s[14:15], exec, s[4:5]
	s_cbranch_execz .LBB0_456
	s_movk_i32 s4, 0x12ff
	v_cmp_lt_u32_e32 vcc, s4, v0
	s_and_saveexec_b64 s[4:5], vcc
	s_xor_b64 s[16:17], exec, s[4:5]
	s_cbranch_execz .LBB0_453
	s_movk_i32 s4, 0x14ff
	v_cmp_lt_u32_e32 vcc, s4, v0
	s_and_saveexec_b64 s[4:5], vcc
	s_xor_b64 s[72:73], exec, s[4:5]
	s_cbranch_execz .LBB0_450
	s_movk_i32 s4, 0x18ff
	v_cmp_lt_u32_e32 vcc, s4, v0
	s_and_saveexec_b64 s[4:5], vcc
	s_xor_b64 s[12:13], exec, s[4:5]
	s_cbranch_execz .LBB0_447
	s_movk_i32 s4, 0x23ff
	v_cmp_lt_u32_e32 vcc, s4, v0
	s_and_saveexec_b64 s[4:5], vcc
	s_xor_b64 s[38:39], exec, s[4:5]
	s_cbranch_execz .LBB0_420
	s_movk_i32 s4, 0x2eff
	v_cmp_lt_u32_e32 vcc, s4, v0
	s_and_saveexec_b64 s[4:5], vcc
	s_xor_b64 s[28:29], exec, s[4:5]
	s_cbranch_execz .LBB0_393
	s_load_dwordx2 s[4:5], s[0:1], 0xd8
	v_lshrrev_b32_e32 v88, 5, v113
	v_lshlrev_b32_e32 v0, 11, v88
	v_sub_u32_e32 v89, v114, v0
	v_add_u32_e32 v2, 0xfff44000, v89
	s_waitcnt lgkmcnt(0)
	s_add_u32 s4, s4, s43
	s_addc_u32 s5, s5, s20
	v_ashrrev_i32_e32 v3, 31, v2
	v_lshl_or_b32 v4, v88, 6, v70
	v_lshl_add_u64 v[2:3], v[2:3], 2, s[4:5]
	v_lshlrev_b32_e32 v0, 2, v72
	v_lshl_add_u64 v[2:3], v[2:3], 0, v[0:1]
	v_lshlrev_b32_e32 v0, 11, v4
	v_lshl_add_u64 v[62:63], v[0:1], 2, v[2:3]
	v_add_co_u32_e32 v6, vcc, s81, v62
	s_mov_b32 s4, 0x28000
	s_nop 0
	v_addc_co_u32_e32 v7, vcc, 0, v63, vcc
	v_add_co_u32_e32 v10, vcc, s57, v62
	global_load_dwordx4 v[2:5], v[62:63], off nt
	s_nop 0
	global_load_dwordx4 v[6:9], v[6:7], off nt
	v_addc_co_u32_e32 v11, vcc, 0, v63, vcc
	v_add_co_u32_e32 v14, vcc, s76, v62
	v_add_u32_e32 v0, 0x410, v73
	s_nop 0
	v_addc_co_u32_e32 v15, vcc, 0, v63, vcc
	global_load_dwordx4 v[10:13], v[10:11], off nt
	s_nop 0
	global_load_dwordx4 v[14:17], v[14:15], off nt
	v_add_co_u32_e32 v18, vcc, s82, v62
	s_nop 1
	v_addc_co_u32_e32 v19, vcc, 0, v63, vcc
	v_add_co_u32_e32 v22, vcc, s4, v62
	s_mov_b32 s4, 0x30000
	s_nop 0
	v_addc_co_u32_e32 v23, vcc, 0, v63, vcc
	global_load_dwordx4 v[18:21], v[18:19], off nt
	s_nop 0
	global_load_dwordx4 v[22:25], v[22:23], off nt
	v_add_co_u32_e32 v26, vcc, s4, v62
	s_mov_b32 s4, 0x38000
	s_nop 0
	v_addc_co_u32_e32 v27, vcc, 0, v63, vcc
	v_add_co_u32_e32 v30, vcc, s4, v62
	s_mov_b32 s4, 0x48000
	s_nop 0
	v_addc_co_u32_e32 v31, vcc, 0, v63, vcc
	global_load_dwordx4 v[26:29], v[26:27], off nt
	s_nop 0
	global_load_dwordx4 v[30:33], v[30:31], off nt
	v_add_co_u32_e32 v34, vcc, s75, v62
	s_nop 1
	v_addc_co_u32_e32 v35, vcc, 0, v63, vcc
	v_add_co_u32_e32 v38, vcc, s4, v62
	s_mov_b32 s4, 0x50000
	s_nop 0
	v_addc_co_u32_e32 v39, vcc, 0, v63, vcc
	global_load_dwordx4 v[34:37], v[34:35], off nt
	s_nop 0
	global_load_dwordx4 v[38:41], v[38:39], off nt
	v_add_co_u32_e32 v42, vcc, s4, v62
	s_mov_b32 s4, 0x58000
	s_nop 0
	v_addc_co_u32_e32 v43, vcc, 0, v63, vcc
	v_add_co_u32_e32 v46, vcc, s4, v62
	s_mov_b32 s4, 0x60000
	s_nop 0
	v_addc_co_u32_e32 v47, vcc, 0, v63, vcc
	global_load_dwordx4 v[42:45], v[42:43], off nt
	s_nop 0
	global_load_dwordx4 v[46:49], v[46:47], off nt
	v_add_co_u32_e32 v50, vcc, s4, v62
	s_mov_b32 s4, 0x68000
	s_nop 0
	v_addc_co_u32_e32 v51, vcc, 0, v63, vcc
	global_load_dwordx4 v[50:53], v[50:51], off nt
	v_add_co_u32_e32 v54, vcc, s4, v62
	s_mov_b32 s4, 0x70000
	s_nop 0
	v_addc_co_u32_e32 v55, vcc, 0, v63, vcc
	global_load_dwordx4 v[54:57], v[54:55], off nt
	v_add_co_u32_e32 v58, vcc, s4, v62
	s_mov_b32 s4, 0x78000
	s_nop 0
	v_addc_co_u32_e32 v59, vcc, 0, v63, vcc
	global_load_dwordx4 v[58:61], v[58:59], off nt
	v_add_co_u32_e32 v62, vcc, s4, v62
	s_nop 1
	v_addc_co_u32_e32 v63, vcc, 0, v63, vcc
	global_load_dwordx4 v[62:65], v[62:63], off nt
	s_waitcnt vmcnt(15)
	ds_write2_b32 v73, v2, v3 offset1:1
	ds_write2_b32 v73, v4, v5 offset0:2 offset1:3
	s_waitcnt vmcnt(14)
	ds_write2_b32 v0, v6, v7 offset1:1
	v_add_u32_e32 v0, 0x418, v73
	ds_write2_b32 v0, v8, v9 offset1:1
	v_add_u32_e32 v0, 0x820, v73
	s_waitcnt vmcnt(13)
	ds_write2_b32 v0, v10, v11 offset1:1
	v_add_u32_e32 v0, 0x828, v73
	ds_write2_b32 v0, v12, v13 offset1:1
	v_add_u32_e32 v0, 0xc30, v73
	s_waitcnt vmcnt(12)
	ds_write2_b32 v0, v14, v15 offset1:1
	v_add_u32_e32 v0, 0xc38, v73
	ds_write2_b32 v0, v16, v17 offset1:1
	v_add_u32_e32 v0, 0x1040, v73
	v_add_u32_e32 v12, 0x400, v93
	s_waitcnt vmcnt(11)
	ds_write2_b32 v0, v18, v19 offset1:1
	v_add_u32_e32 v0, 0x1048, v73
	ds_write2_b32 v0, v20, v21 offset1:1
	v_add_u32_e32 v0, 0x1450, v73
	s_waitcnt vmcnt(10)
	ds_write2_b32 v0, v22, v23 offset1:1
	v_add_u32_e32 v0, 0x1458, v73
	ds_write2_b32 v0, v24, v25 offset1:1
	v_add_u32_e32 v0, 0x1860, v73
	s_waitcnt vmcnt(9)
	ds_write2_b32 v0, v26, v27 offset1:1
	v_add_u32_e32 v0, 0x1868, v73
	ds_write2_b32 v0, v28, v29 offset1:1
	v_add_u32_e32 v0, 0x1c70, v73
	s_waitcnt vmcnt(8)
	ds_write2_b32 v0, v30, v31 offset1:1
	v_add_u32_e32 v0, 0x1c78, v73
	ds_write2_b32 v0, v32, v33 offset1:1
	v_add_u32_e32 v0, 0x2080, v73
	s_waitcnt vmcnt(7)
	ds_write2_b32 v0, v34, v35 offset1:1
	v_add_u32_e32 v0, 0x2088, v73
	ds_write2_b32 v0, v36, v37 offset1:1
	v_add_u32_e32 v0, 0x2490, v73
	s_waitcnt vmcnt(6)
	ds_write2_b32 v0, v38, v39 offset1:1
	v_add_u32_e32 v0, 0x2498, v73
	ds_write2_b32 v0, v40, v41 offset1:1
	v_add_u32_e32 v0, 0x28a0, v73
	s_waitcnt vmcnt(5)
	ds_write2_b32 v0, v42, v43 offset1:1
	v_add_u32_e32 v0, 0x28a8, v73
	ds_write2_b32 v0, v44, v45 offset1:1
	v_add_u32_e32 v0, 0x2cb0, v73
	s_waitcnt vmcnt(4)
; DI unsigned cvt_pk_bf16(float lo, float hi) { unsigned r; asm volatile("v_cvt_pk_bf16_f32 %0, %1, %2" : "=v"(r) : "v"(lo), "v"(hi)); return r; }
; #define LDS_WAIT() asm volatile("s_waitcnt lgkmcnt(0)" ::: "memory")
; DI void tr_item(const float* W, int N, const float* scale, bf16_t* WT, int ldk, int koff, int gu, int which, float* scr, int item, int lane) {
;     ...
;     LDS_WAIT();
;     const int c = lane & 7;
; #pragma unroll
;     for (int j = 0; j < 8; ++j) { const int n = (lane >> 3) + 8 * j; const float* s = scr + (8 * c) * 65 + n;
;         u32x4 o; o.x = cvt_pk_bf16(s[0 * 65], s[1 * 65]); o.y = cvt_pk_bf16(s[2 * 65], s[3 * 65]); o.z = cvt_pk_bf16(s[4 * 65], s[5 * 65]); o.w = cvt_pk_bf16(s[6 * 65], s[7 * 65]);
;         const int nn = n0 + n; const int drow = gu ? (((nn >> 7) << 8) + which * 128 + (nn & 127)) : nn;
;         *(u32x4*)(WT + (size_t)drow * ldk + koff + k0 + 8 * c) = o; }
;     LDS_WAIT();
	ds_write2_b32 v0, v46, v47 offset1:1
	v_add_u32_e32 v0, 0x2cb8, v73
	ds_write2_b32 v0, v48, v49 offset1:1
	v_add_u32_e32 v0, 0x30c0, v73
	s_waitcnt vmcnt(3)
	ds_write2_b32 v0, v50, v51 offset1:1
	v_add_u32_e32 v0, 0x30c8, v73
	ds_write2_b32 v0, v52, v53 offset1:1
	v_add_u32_e32 v0, 0x34d0, v73
	s_waitcnt vmcnt(2)
	ds_write2_b32 v0, v54, v55 offset1:1
	v_add_u32_e32 v0, 0x34d8, v73
	ds_write2_b32 v0, v56, v57 offset1:1
	v_add_u32_e32 v0, 0x38e0, v73
	s_waitcnt vmcnt(1)
	ds_write2_b32 v0, v58, v59 offset1:1
	v_add_u32_e32 v0, 0x38e8, v73
	ds_write2_b32 v0, v60, v61 offset1:1
	v_add_u32_e32 v0, 0x3cf0, v73
	s_waitcnt vmcnt(0)
	ds_write2_b32 v0, v62, v63 offset1:1
	v_add_u32_e32 v0, 0x3cf8, v73
	ds_write2_b32 v0, v64, v65 offset1:1
	s_waitcnt lgkmcnt(0)
	ds_read2_b32 v[2:3], v93 offset1:65
	s_waitcnt lgkmcnt(0)
	v_cvt_pk_bf16_f32 v2, v2, v3
	ds_read2_b32 v[4:5], v93 offset0:130 offset1:195
	v_lshlrev_b32_e32 v0, 7, v88
	s_waitcnt lgkmcnt(0)
	v_cvt_pk_bf16_f32 v3, v4, v5
	ds_read2_b32 v[4:5], v12 offset0:4 offset1:69
	v_lshl_add_u64 v[8:9], v[76:77], 0, v[0:1]
	v_add_u32_e32 v0, v89, v121
	s_waitcnt lgkmcnt(0)
	v_cvt_pk_bf16_f32 v4, v4, v5
	ds_read2_b32 v[6:7], v12 offset0:134 offset1:199
	s_waitcnt lgkmcnt(0)
	v_cvt_pk_bf16_f32 v5, v6, v7
	v_mad_i64_i32 v[10:11], s[4:5], v0, s31, v[8:9]
	ds_read2_b32 v[6:7], v93 offset0:8 offset1:73
	global_store_dwordx4 v[10:11], v[2:5], off
	v_add_u32_e32 v0, v89, v120
	v_mad_i64_i32 v[10:11], s[4:5], v0, s31, v[8:9]
	s_waitcnt lgkmcnt(0)
	v_cvt_pk_bf16_f32 v2, v6, v7
	ds_read2_b32 v[4:5], v93 offset0:138 offset1:203
	s_waitcnt lgkmcnt(0)
	v_cvt_pk_bf16_f32 v3, v4, v5
	ds_read2_b32 v[4:5], v12 offset0:12 offset1:77
	s_waitcnt lgkmcnt(0)
	v_cvt_pk_bf16_f32 v4, v4, v5
	ds_read2_b32 v[6:7], v12 offset0:142 offset1:207
	s_waitcnt lgkmcnt(0)
	v_cvt_pk_bf16_f32 v5, v6, v7
	ds_read2_b32 v[6:7], v93 offset0:16 offset1:81
	global_store_dwordx4 v[10:11], v[2:5], off
	v_add_u32_e32 v0, v89, v119
	v_mad_i64_i32 v[10:11], s[4:5], v0, s31, v[8:9]
	s_waitcnt lgkmcnt(0)
	v_cvt_pk_bf16_f32 v2, v6, v7
	ds_read2_b32 v[4:5], v93 offset0:146 offset1:211
	s_waitcnt lgkmcnt(0)
	v_cvt_pk_bf16_f32 v3, v4, v5
	ds_read2_b32 v[4:5], v12 offset0:20 offset1:85
	s_waitcnt lgkmcnt(0)
	v_cvt_pk_bf16_f32 v4, v4, v5
	ds_read2_b32 v[6:7], v12 offset0:150 offset1:215
	s_waitcnt lgkmcnt(0)
	v_cvt_pk_bf16_f32 v5, v6, v7
	ds_read2_b32 v[6:7], v93 offset0:24 offset1:89
	global_store_dwordx4 v[10:11], v[2:5], off
	v_add_u32_e32 v0, v89, v118
	v_mad_i64_i32 v[10:11], s[4:5], v0, s31, v[8:9]
	s_waitcnt lgkmcnt(0)
	v_cvt_pk_bf16_f32 v2, v6, v7
	ds_read2_b32 v[4:5], v93 offset0:154 offset1:219
	s_waitcnt lgkmcnt(0)
	v_cvt_pk_bf16_f32 v3, v4, v5
	ds_read2_b32 v[4:5], v12 offset0:28 offset1:93
	s_waitcnt lgkmcnt(0)
	v_cvt_pk_bf16_f32 v4, v4, v5
	ds_read2_b32 v[6:7], v12 offset0:158 offset1:223
	s_waitcnt lgkmcnt(0)
	v_cvt_pk_bf16_f32 v5, v6, v7
	ds_read2_b32 v[6:7], v93 offset0:32 offset1:97
	global_store_dwordx4 v[10:11], v[2:5], off
	v_add_u32_e32 v0, v89, v117
	v_mad_i64_i32 v[10:11], s[4:5], v0, s31, v[8:9]
	s_waitcnt lgkmcnt(0)
	v_cvt_pk_bf16_f32 v2, v6, v7
	ds_read2_b32 v[4:5], v93 offset0:162 offset1:227
	s_waitcnt lgkmcnt(0)
	v_cvt_pk_bf16_f32 v3, v4, v5
	ds_read2_b32 v[4:5], v12 offset0:36 offset1:101
	s_waitcnt lgkmcnt(0)
	v_cvt_pk_bf16_f32 v4, v4, v5
	ds_read2_b32 v[6:7], v12 offset0:166 offset1:231
	s_waitcnt lgkmcnt(0)
	v_cvt_pk_bf16_f32 v5, v6, v7
	ds_read2_b32 v[6:7], v93 offset0:40 offset1:105
	global_store_dwordx4 v[10:11], v[2:5], off
	v_add_u32_e32 v0, v89, v116
	v_mad_i64_i32 v[10:11], s[4:5], v0, s31, v[8:9]
	s_waitcnt lgkmcnt(0)
	v_cvt_pk_bf16_f32 v2, v6, v7
	ds_read2_b32 v[4:5], v93 offset0:170 offset1:235
	s_waitcnt lgkmcnt(0)
	v_cvt_pk_bf16_f32 v3, v4, v5
	ds_read2_b32 v[4:5], v12 offset0:44 offset1:109
	s_waitcnt lgkmcnt(0)
	v_cvt_pk_bf16_f32 v4, v4, v5
	ds_read2_b32 v[6:7], v12 offset0:174 offset1:239
	s_waitcnt lgkmcnt(0)
	v_cvt_pk_bf16_f32 v5, v6, v7
	ds_read2_b32 v[6:7], v93 offset0:48 offset1:113
	global_store_dwordx4 v[10:11], v[2:5], off
	v_add_u32_e32 v0, v89, v115
	v_mad_i64_i32 v[10:11], s[4:5], v0, s31, v[8:9]
	s_waitcnt lgkmcnt(0)
	v_cvt_pk_bf16_f32 v2, v6, v7
	ds_read2_b32 v[4:5], v93 offset0:178 offset1:243
	s_waitcnt lgkmcnt(0)
	v_cvt_pk_bf16_f32 v3, v4, v5
	ds_read2_b32 v[4:5], v12 offset0:52 offset1:117
	s_waitcnt lgkmcnt(0)
	v_cvt_pk_bf16_f32 v4, v4, v5
	ds_read2_b32 v[6:7], v12 offset0:182 offset1:247
	s_waitcnt lgkmcnt(0)
	v_cvt_pk_bf16_f32 v5, v6, v7
	ds_read2_b32 v[6:7], v93 offset0:56 offset1:121
	global_store_dwordx4 v[10:11], v[2:5], off
	v_add_u32_e32 v0, v89, v112
	s_waitcnt lgkmcnt(0)
	v_cvt_pk_bf16_f32 v2, v6, v7
	ds_read2_b32 v[4:5], v93 offset0:186 offset1:251
	s_waitcnt lgkmcnt(0)
	v_cvt_pk_bf16_f32 v3, v4, v5
	ds_read2_b32 v[4:5], v12 offset0:60 offset1:125
	s_waitcnt lgkmcnt(0)
	v_cvt_pk_bf16_f32 v4, v4, v5
	ds_read2_b32 v[6:7], v12 offset0:190 offset1:255
	s_waitcnt lgkmcnt(0)
	v_cvt_pk_bf16_f32 v5, v6, v7
	v_mad_i64_i32 v[6:7], s[4:5], v0, s31, v[8:9]
	global_store_dwordx4 v[6:7], v[2:5], off
	s_waitcnt lgkmcnt(0)
; DI void tr_item(const float* W, int N, const float* scale, bf16_t* WT, int ldk, int koff, int gu, int which, float* scr, int item, int lane) {
;     const int nblk = N >> 6, kb = item / nblk, nb = item - kb * nblk, k0 = 64 * kb, n0 = 64 * nb;
;     const int lr = lane >> 4, lc = (lane & 15) * 4;
;     f32x4 v[16];
; #pragma unroll
;     for (int i = 0; i < 16; ++i) v[i] = *(const f32x4*)(W + (size_t)(k0 + 4 * i + lr) * N + n0 + lc);
; #pragma unroll
;     for (int i = 0; i < 16; ++i) { const int kk = 4 * i + lr; const float sc = scale ? scale[k0 + kk] : 1.f; float* d = scr + kk * 65 + lc;
;         d[0] = v[i].x * sc; d[1] = v[i].y * sc; d[2] = v[i].z * sc; d[3] = v[i].w * sc; }
; DI void conv_phase(PP P, int l, unsigned char* lds, int G, int cid) {
;     ...
;         if (r < I7) { tr_item(P->in[26] + (size_t)l * DM * DFF, DFF, n2, (bf16_t*)(ws + WS_WGU), DM, 0, 1, 1, scr, r, lane); continue; } r -= I7;
.LBB0_393:
	s_andn2_saveexec_b64 s[28:29], s[28:29]
	s_cbranch_execz .LBB0_419
	s_load_dwordx2 s[4:5], s[0:1], 0xd0
	v_add_u32_e32 v0, 0xb00, v113
	v_mul_u32_u24_e32 v2, 0xba2f, v0
	v_lshrrev_b32_e32 v2, 22, v2
	s_movk_i32 s6, 0xffa8
	v_mad_i32_i24 v91, v2, s6, v0
	s_waitcnt lgkmcnt(0)
	s_add_u32 s4, s4, s43
	v_lshlrev_b32_e32 v88, 6, v91
	s_addc_u32 s5, s5, s20
	v_lshlrev_b32_e32 v90, 6, v2
	v_ashrrev_i32_e32 v89, 31, v88
	v_or_b32_e32 v158, v90, v70
	v_lshl_add_u64 v[2:3], v[88:89], 2, s[4:5]
	v_lshlrev_b32_e32 v0, 2, v72
	v_lshl_add_u64 v[2:3], v[2:3], 0, v[0:1]
	s_movk_i32 s4, 0x5800
	v_mul_u32_u24_e32 v0, 0x1600, v158
	v_mad_u64_u32 v[4:5], s[4:5], v158, s4, v[2:3]
	v_lshlrev_b32_e32 v0, 2, v0
	v_lshl_add_u64 v[2:3], v[2:3], 0, v[0:1]
	s_mov_b32 s4, 0x16000
	v_add_co_u32_e32 v6, vcc, s4, v2
	s_mov_b32 s4, 0x2c000
	s_nop 0
	v_addc_co_u32_e32 v7, vcc, 0, v3, vcc
	global_load_dwordx4 v[62:65], v[4:5], off nt
	global_load_dwordx4 v[58:61], v[6:7], off nt
	v_add_co_u32_e32 v4, vcc, s4, v2
	s_mov_b32 s4, 0x42000
	s_nop 0
	v_addc_co_u32_e32 v5, vcc, 0, v3, vcc
	v_add_co_u32_e32 v6, vcc, s4, v2
	s_mov_b32 s4, 0x58000
	s_nop 0
	v_addc_co_u32_e32 v7, vcc, 0, v3, vcc
	global_load_dwordx4 v[54:57], v[4:5], off nt
	global_load_dwordx4 v[50:53], v[6:7], off nt
	v_add_co_u32_e32 v4, vcc, s4, v2
	s_mov_b32 s4, 0x6e000
	s_nop 0
	v_addc_co_u32_e32 v5, vcc, 0, v3, vcc
	v_add_co_u32_e32 v6, vcc, s4, v2
	s_mov_b32 s4, 0x84000
	s_nop 0
	v_addc_co_u32_e32 v7, vcc, 0, v3, vcc
	global_load_dwordx4 v[46:49], v[4:5], off nt
	global_load_dwordx4 v[42:45], v[6:7], off nt
	v_add_co_u32_e32 v4, vcc, s4, v2
	s_mov_b32 s4, 0x9a000
	s_nop 0
	v_addc_co_u32_e32 v5, vcc, 0, v3, vcc
	v_add_co_u32_e32 v6, vcc, s4, v2
	s_mov_b32 s4, 0xb0000
	s_nop 0
	v_addc_co_u32_e32 v7, vcc, 0, v3, vcc
	global_load_dwordx4 v[38:41], v[4:5], off nt
	global_load_dwordx4 v[34:37], v[6:7], off nt
	v_add_co_u32_e32 v4, vcc, s4, v2
	s_mov_b32 s4, 0xc6000
	s_nop 0
	v_addc_co_u32_e32 v5, vcc, 0, v3, vcc
	v_add_co_u32_e32 v6, vcc, s4, v2
	s_mov_b32 s4, 0xdc000
	s_nop 0
	v_addc_co_u32_e32 v7, vcc, 0, v3, vcc
	global_load_dwordx4 v[30:33], v[4:5], off nt
	global_load_dwordx4 v[26:29], v[6:7], off nt
	v_add_co_u32_e32 v4, vcc, s4, v2
	s_mov_b32 s4, 0xf2000
	s_nop 0
	v_addc_co_u32_e32 v5, vcc, 0, v3, vcc
	v_add_co_u32_e32 v6, vcc, s4, v2
	s_mov_b32 s4, 0x108000
	s_nop 0
	v_addc_co_u32_e32 v7, vcc, 0, v3, vcc
	global_load_dwordx4 v[22:25], v[4:5], off nt
	global_load_dwordx4 v[18:21], v[6:7], off nt
	v_add_co_u32_e32 v4, vcc, s4, v2
	v_cndmask_b32_e64 v0, 0, 1, s[52:53]
	s_nop 0
	v_addc_co_u32_e32 v5, vcc, 0, v3, vcc
	v_add_co_u32_e32 v6, vcc, 0x11e000, v2
	v_cmp_ne_u32_e64 s[40:41], 1, v0
	s_nop 0
	v_addc_co_u32_e32 v7, vcc, 0, v3, vcc
	global_load_dwordx4 v[14:17], v[4:5], off nt
	global_load_dwordx4 v[10:13], v[6:7], off nt
	v_add_co_u32_e32 v4, vcc, 0x134000, v2
	v_add_lshl_u32 v89, v90, v70, 2
	s_nop 0
	v_addc_co_u32_e32 v5, vcc, 0, v3, vcc
	v_add_co_u32_e32 v2, vcc, 0x14a000, v2
	s_nop 1
	v_addc_co_u32_e32 v3, vcc, 0, v3, vcc
	global_load_dwordx4 v[6:9], v[4:5], off nt
	s_nop 0
	global_load_dwordx4 v[2:5], v[2:3], off nt
	s_andn2_b64 vcc, exec, s[52:53]
	s_cbranch_vccnz .LBB0_499
	v_lshlrev_b32_e32 v0, 2, v158
	global_load_dword v0, v0, s[48:49]
	s_waitcnt vmcnt(0)
	v_pk_mul_f32 v[158:159], v[62:63], v[0:1] op_sel_hi:[1,0]
	ds_write2_b32 v73, v158, v159 offset1:1
	v_pk_mul_f32 v[158:159], v[64:65], v[0:1] op_sel_hi:[1,0]
	global_load_dword v0, v89, s[48:49] offset:16
	ds_write2_b32 v73, v158, v159 offset0:2 offset1:3
	s_cbranch_execnz .LBB0_397

; DI void tr_item(const float* W, int N, const float* scale, bf16_t* WT, int ldk, int koff, int gu, int which, float* scr, int item, int lane) {
;     const int nblk = N >> 6, kb = item / nblk, nb = item - kb * nblk, k0 = 64 * kb, n0 = 64 * nb;
;     const int lr = lane >> 4, lc = (lane & 15) * 4;
;     f32x4 v[16];
; #pragma unroll
;     for (int i = 0; i < 16; ++i) v[i] = *(const f32x4*)(W + (size_t)(k0 + 4 * i + lr) * N + n0 + lc);
; #pragma unroll
;     for (int i = 0; i < 16; ++i) { const int kk = 4 * i + lr; const float sc = scale ? scale[k0 + kk] : 1.f; float* d = scr + kk * 65 + lc;
;         d[0] = v[i].x * sc; d[1] = v[i].y * sc; d[2] = v[i].z * sc; d[3] = v[i].w * sc; }
; DI void conv_phase(PP P, int l, unsigned char* lds, int G, int cid) {
;     ...
;         if (r < I6) { tr_item(P->in[25] + (size_t)l * DM * DFF, DFF, n2, (bf16_t*)(ws + WS_WGU), DM, 0, 1, 0, scr, r, lane); continue; } r -= I6;
.LBB0_420:
	s_andn2_saveexec_b64 s[38:39], s[38:39]
	s_cbranch_execz .LBB0_446
	s_load_dwordx2 s[4:5], s[0:1], 0xc8
	v_add_u32_e32 v0, 0x1600, v113
	v_mul_u32_u24_e32 v2, 0xba2f, v0
	v_lshrrev_b32_e32 v2, 22, v2
	s_movk_i32 s6, 0xffa8
	v_mad_i32_i24 v91, v2, s6, v0
	s_waitcnt lgkmcnt(0)
	s_add_u32 s4, s4, s43
	v_lshlrev_b32_e32 v88, 6, v91
	s_addc_u32 s5, s5, s20
	v_lshlrev_b32_e32 v90, 6, v2
	v_ashrrev_i32_e32 v89, 31, v88
	v_or_b32_e32 v158, v90, v70
	v_lshl_add_u64 v[2:3], v[88:89], 2, s[4:5]
	v_lshlrev_b32_e32 v0, 2, v72
	v_lshl_add_u64 v[2:3], v[2:3], 0, v[0:1]
	s_movk_i32 s4, 0x5800
	v_mul_u32_u24_e32 v0, 0x1600, v158
	v_mad_u64_u32 v[4:5], s[4:5], v158, s4, v[2:3]
	v_lshlrev_b32_e32 v0, 2, v0
	v_lshl_add_u64 v[2:3], v[2:3], 0, v[0:1]
	s_mov_b32 s4, 0x16000
	v_add_co_u32_e32 v6, vcc, s4, v2
	s_mov_b32 s4, 0x2c000
	s_nop 0
	v_addc_co_u32_e32 v7, vcc, 0, v3, vcc
	global_load_dwordx4 v[62:65], v[4:5], off nt
	global_load_dwordx4 v[58:61], v[6:7], off nt
	v_add_co_u32_e32 v4, vcc, s4, v2
	s_mov_b32 s4, 0x42000
	s_nop 0
	v_addc_co_u32_e32 v5, vcc, 0, v3, vcc
	v_add_co_u32_e32 v6, vcc, s4, v2
	s_mov_b32 s4, 0x58000
	s_nop 0
	v_addc_co_u32_e32 v7, vcc, 0, v3, vcc
	global_load_dwordx4 v[54:57], v[4:5], off nt
	global_load_dwordx4 v[50:53], v[6:7], off nt
	v_add_co_u32_e32 v4, vcc, s4, v2
	s_mov_b32 s4, 0x6e000
	s_nop 0
	v_addc_co_u32_e32 v5, vcc, 0, v3, vcc
	v_add_co_u32_e32 v6, vcc, s4, v2
	s_mov_b32 s4, 0x84000
	s_nop 0
	v_addc_co_u32_e32 v7, vcc, 0, v3, vcc
	global_load_dwordx4 v[46:49], v[4:5], off nt
	global_load_dwordx4 v[42:45], v[6:7], off nt
	v_add_co_u32_e32 v4, vcc, s4, v2
	s_mov_b32 s4, 0x9a000
	s_nop 0
	v_addc_co_u32_e32 v5, vcc, 0, v3, vcc
	v_add_co_u32_e32 v6, vcc, s4, v2
	s_mov_b32 s4, 0xb0000
	s_nop 0
	v_addc_co_u32_e32 v7, vcc, 0, v3, vcc
	global_load_dwordx4 v[38:41], v[4:5], off nt
	global_load_dwordx4 v[34:37], v[6:7], off nt
	v_add_co_u32_e32 v4, vcc, s4, v2
	s_mov_b32 s4, 0xc6000
	s_nop 0
	v_addc_co_u32_e32 v5, vcc, 0, v3, vcc
	v_add_co_u32_e32 v6, vcc, s4, v2
	s_mov_b32 s4, 0xdc000
	s_nop 0
	v_addc_co_u32_e32 v7, vcc, 0, v3, vcc
	global_load_dwordx4 v[30:33], v[4:5], off nt
	global_load_dwordx4 v[26:29], v[6:7], off nt
	v_add_co_u32_e32 v4, vcc, s4, v2
	s_mov_b32 s4, 0xf2000
	s_nop 0
	v_addc_co_u32_e32 v5, vcc, 0, v3, vcc
	v_add_co_u32_e32 v6, vcc, s4, v2
	s_mov_b32 s4, 0x108000
	s_nop 0
	v_addc_co_u32_e32 v7, vcc, 0, v3, vcc
	global_load_dwordx4 v[22:25], v[4:5], off nt
	global_load_dwordx4 v[18:21], v[6:7], off nt
	v_add_co_u32_e32 v4, vcc, s4, v2
	v_cndmask_b32_e64 v0, 0, 1, s[52:53]
	s_nop 0
	v_addc_co_u32_e32 v5, vcc, 0, v3, vcc
	v_add_co_u32_e32 v6, vcc, 0x11e000, v2
	v_cmp_ne_u32_e64 s[40:41], 1, v0
	s_nop 0
	v_addc_co_u32_e32 v7, vcc, 0, v3, vcc
	global_load_dwordx4 v[14:17], v[4:5], off nt
	global_load_dwordx4 v[10:13], v[6:7], off nt
	v_add_co_u32_e32 v4, vcc, 0x134000, v2
	v_add_lshl_u32 v89, v90, v70, 2
	s_nop 0
	v_addc_co_u32_e32 v5, vcc, 0, v3, vcc
	v_add_co_u32_e32 v2, vcc, 0x14a000, v2
	s_nop 1
	v_addc_co_u32_e32 v3, vcc, 0, v3, vcc
	global_load_dwordx4 v[6:9], v[4:5], off nt
	s_nop 0
	global_load_dwordx4 v[2:5], v[2:3], off nt
	s_andn2_b64 vcc, exec, s[52:53]
	s_cbranch_vccnz .LBB0_491
	v_lshlrev_b32_e32 v0, 2, v158
	global_load_dword v0, v0, s[48:49]
	s_waitcnt vmcnt(0)
	v_pk_mul_f32 v[158:159], v[62:63], v[0:1] op_sel_hi:[1,0]
	ds_write2_b32 v73, v158, v159 offset1:1
	v_pk_mul_f32 v[158:159], v[64:65], v[0:1] op_sel_hi:[1,0]
	global_load_dword v0, v89, s[48:49] offset:16
	ds_write2_b32 v73, v158, v159 offset0:2 offset1:3
	s_cbranch_execnz .LBB0_424

; DI void tr_item(const float* W, int N, const float* scale, bf16_t* WT, int ldk, int koff, int gu, int which, float* scr, int item, int lane) {
;     const int nblk = N >> 6, kb = item / nblk, nb = item - kb * nblk, k0 = 64 * kb, n0 = 64 * nb;
;     const int lr = lane >> 4, lc = (lane & 15) * 4;
;     f32x4 v[16];
; #pragma unroll
;     for (int i = 0; i < 16; ++i) v[i] = *(const f32x4*)(W + (size_t)(k0 + 4 * i + lr) * N + n0 + lc);
; #pragma unroll
;     for (int i = 0; i < 16; ++i) { const int kk = 4 * i + lr; const float sc = scale ? scale[k0 + kk] : 1.f; float* d = scr + kk * 65 + lc;
;         d[0] = v[i].x * sc; d[1] = v[i].y * sc; d[2] = v[i].z * sc; d[3] = v[i].w * sc; }
; DI void conv_phase(PP P, int l, unsigned char* lds, int G, int cid) {
;     ...
;         if (r < I5) { tr_item(P->in[22] + (size_t)l * DM * DM, DM, nullptr, (bf16_t*)(ws + WS_WOUT), DM, 0, 0, 0, scr, r, lane); continue; } r -= I5;
.LBB0_447:
	s_andn2_saveexec_b64 s[12:13], s[12:13]
	s_cbranch_execz .LBB0_449
	s_load_dwordx2 s[4:5], s[0:1], 0xb0
	v_mov_b32_e32 v0, 0x3400
	v_lshl_add_u32 v0, v113, 1, v0
	v_lshlrev_b32_e32 v2, 6, v123
	v_and_b32_e32 v88, 0xffffffc0, v0
	v_and_b32_e32 v0, 0xfffff800, v2
	v_sub_u32_e32 v90, v114, v0
	s_waitcnt lgkmcnt(0)
	s_add_u32 s4, s4, s54
	v_add_u32_e32 v2, 0xfffac000, v90
	s_addc_u32 s5, s5, s55
	v_ashrrev_i32_e32 v3, 31, v2
	v_or_b32_e32 v4, v88, v70
	v_lshl_add_u64 v[2:3], v[2:3], 2, s[4:5]
	v_lshlrev_b32_e32 v0, 2, v72
	v_lshl_add_u64 v[2:3], v[2:3], 0, v[0:1]
	v_lshlrev_b32_e32 v0, 11, v4
	v_lshl_add_u64 v[62:63], v[0:1], 2, v[2:3]
	v_add_co_u32_e32 v6, vcc, s81, v62
	s_mov_b32 s4, 0x28000
	s_nop 0
	v_addc_co_u32_e32 v7, vcc, 0, v63, vcc
	v_add_co_u32_e32 v10, vcc, s57, v62
	global_load_dwordx4 v[2:5], v[62:63], off nt
	s_nop 0
	global_load_dwordx4 v[6:9], v[6:7], off nt
	v_addc_co_u32_e32 v11, vcc, 0, v63, vcc
	v_add_co_u32_e32 v14, vcc, s76, v62
	v_add_u32_e32 v0, 0x410, v73
	s_nop 0
	v_addc_co_u32_e32 v15, vcc, 0, v63, vcc
	global_load_dwordx4 v[10:13], v[10:11], off nt
	s_nop 0
	global_load_dwordx4 v[14:17], v[14:15], off nt
	v_add_co_u32_e32 v18, vcc, s82, v62
	v_mov_b32_e32 v89, v1
	s_nop 0
	v_addc_co_u32_e32 v19, vcc, 0, v63, vcc
	v_add_co_u32_e32 v22, vcc, s4, v62
	s_mov_b32 s4, 0x30000
	s_nop 0
	v_addc_co_u32_e32 v23, vcc, 0, v63, vcc
	global_load_dwordx4 v[18:21], v[18:19], off nt
	s_nop 0
	global_load_dwordx4 v[22:25], v[22:23], off nt
	v_add_co_u32_e32 v26, vcc, s4, v62
	s_mov_b32 s4, 0x38000
	s_nop 0
	v_addc_co_u32_e32 v27, vcc, 0, v63, vcc
	v_add_co_u32_e32 v30, vcc, s4, v62
	s_mov_b32 s4, 0x48000
	s_nop 0
	v_addc_co_u32_e32 v31, vcc, 0, v63, vcc
	global_load_dwordx4 v[26:29], v[26:27], off nt
	s_nop 0
	global_load_dwordx4 v[30:33], v[30:31], off nt
	v_add_co_u32_e32 v34, vcc, s75, v62
	s_nop 1
	v_addc_co_u32_e32 v35, vcc, 0, v63, vcc
	v_add_co_u32_e32 v38, vcc, s4, v62
	s_mov_b32 s4, 0x50000
	s_nop 0
	v_addc_co_u32_e32 v39, vcc, 0, v63, vcc
	global_load_dwordx4 v[34:37], v[34:35], off nt
	s_nop 0
	global_load_dwordx4 v[38:41], v[38:39], off nt
	v_add_co_u32_e32 v42, vcc, s4, v62
	s_mov_b32 s4, 0x58000
	s_nop 0
	v_addc_co_u32_e32 v43, vcc, 0, v63, vcc
	v_add_co_u32_e32 v46, vcc, s4, v62
	s_mov_b32 s4, 0x60000
	s_nop 0
	v_addc_co_u32_e32 v47, vcc, 0, v63, vcc
	global_load_dwordx4 v[42:45], v[42:43], off nt
	s_nop 0
	global_load_dwordx4 v[46:49], v[46:47], off nt
	v_add_co_u32_e32 v50, vcc, s4, v62
	s_mov_b32 s4, 0x68000
	s_nop 0
	v_addc_co_u32_e32 v51, vcc, 0, v63, vcc
	global_load_dwordx4 v[50:53], v[50:51], off nt
	v_add_co_u32_e32 v54, vcc, s4, v62
	s_mov_b32 s4, 0x70000
	s_nop 0
	v_addc_co_u32_e32 v55, vcc, 0, v63, vcc
	global_load_dwordx4 v[54:57], v[54:55], off nt
	v_add_co_u32_e32 v58, vcc, s4, v62
	s_mov_b32 s4, 0x78000
	s_nop 0
	v_addc_co_u32_e32 v59, vcc, 0, v63, vcc
	global_load_dwordx4 v[58:61], v[58:59], off nt
	v_add_co_u32_e32 v62, vcc, s4, v62
	s_nop 1
	v_addc_co_u32_e32 v63, vcc, 0, v63, vcc
	global_load_dwordx4 v[62:65], v[62:63], off nt
	s_waitcnt vmcnt(15)
	ds_write2_b32 v73, v2, v3 offset1:1
	ds_write2_b32 v73, v4, v5 offset0:2 offset1:3
	s_waitcnt vmcnt(14)
	ds_write2_b32 v0, v6, v7 offset1:1
	v_add_u32_e32 v0, 0x418, v73
	ds_write2_b32 v0, v8, v9 offset1:1
	v_add_u32_e32 v0, 0x820, v73
	v_lshl_add_u64 v[8:9], v[88:89], 1, v[80:81]
	s_waitcnt vmcnt(13)
	ds_write2_b32 v0, v10, v11 offset1:1
	v_add_u32_e32 v0, 0x828, v73
	ds_write2_b32 v0, v12, v13 offset1:1
	v_add_u32_e32 v0, 0xc30, v73
	s_waitcnt vmcnt(12)
	ds_write2_b32 v0, v14, v15 offset1:1
	v_add_u32_e32 v0, 0xc38, v73
	ds_write2_b32 v0, v16, v17 offset1:1
	v_add_u32_e32 v0, 0x1040, v73
	s_waitcnt vmcnt(11)
	ds_write2_b32 v0, v18, v19 offset1:1
	v_add_u32_e32 v0, 0x1048, v73
	ds_write2_b32 v0, v20, v21 offset1:1
	v_add_u32_e32 v0, 0x1450, v73
	s_waitcnt vmcnt(10)
	ds_write2_b32 v0, v22, v23 offset1:1
	v_add_u32_e32 v0, 0x1458, v73
	ds_write2_b32 v0, v24, v25 offset1:1
	v_add_u32_e32 v0, 0x1860, v73
	s_waitcnt vmcnt(9)
	ds_write2_b32 v0, v26, v27 offset1:1
	v_add_u32_e32 v0, 0x1868, v73
	ds_write2_b32 v0, v28, v29 offset1:1
	v_add_u32_e32 v0, 0x1c70, v73
	s_waitcnt vmcnt(8)
	ds_write2_b32 v0, v30, v31 offset1:1
	v_add_u32_e32 v0, 0x1c78, v73
	ds_write2_b32 v0, v32, v33 offset1:1
	v_add_u32_e32 v0, 0x2080, v73
	s_waitcnt vmcnt(7)
	ds_write2_b32 v0, v34, v35 offset1:1
	v_add_u32_e32 v0, 0x2088, v73
	ds_write2_b32 v0, v36, v37 offset1:1
	v_add_u32_e32 v0, 0x2490, v73
	s_waitcnt vmcnt(6)
	ds_write2_b32 v0, v38, v39 offset1:1
	v_add_u32_e32 v0, 0x2498, v73
	ds_write2_b32 v0, v40, v41 offset1:1
	v_add_u32_e32 v0, 0x28a0, v73
	s_waitcnt vmcnt(5)
	ds_write2_b32 v0, v42, v43 offset1:1
	v_add_u32_e32 v0, 0x28a8, v73
	ds_write2_b32 v0, v44, v45 offset1:1
	v_add_u32_e32 v0, 0x2cb0, v73
	s_waitcnt vmcnt(4)
	ds_write2_b32 v0, v46, v47 offset1:1
	v_add_u32_e32 v0, 0x2cb8, v73
	ds_write2_b32 v0, v48, v49 offset1:1
	v_add_u32_e32 v0, 0x30c0, v73
	s_waitcnt vmcnt(3)
	ds_write2_b32 v0, v50, v51 offset1:1
	v_add_u32_e32 v0, 0x30c8, v73
	ds_write2_b32 v0, v52, v53 offset1:1
	v_add_u32_e32 v0, 0x34d0, v73
	s_waitcnt vmcnt(2)
; DI unsigned cvt_pk_bf16(float lo, float hi) { unsigned r; asm volatile("v_cvt_pk_bf16_f32 %0, %1, %2" : "=v"(r) : "v"(lo), "v"(hi)); return r; }
; #define LDS_WAIT() asm volatile("s_waitcnt lgkmcnt(0)" ::: "memory")
; DI void tr_item(const float* W, int N, const float* scale, bf16_t* WT, int ldk, int koff, int gu, int which, float* scr, int item, int lane) {
;     ...
;     LDS_WAIT();
;     const int c = lane & 7;
; #pragma unroll
;     for (int j = 0; j < 8; ++j) { const int n = (lane >> 3) + 8 * j; const float* s = scr + (8 * c) * 65 + n;
;         u32x4 o; o.x = cvt_pk_bf16(s[0 * 65], s[1 * 65]); o.y = cvt_pk_bf16(s[2 * 65], s[3 * 65]); o.z = cvt_pk_bf16(s[4 * 65], s[5 * 65]); o.w = cvt_pk_bf16(s[6 * 65], s[7 * 65]);
;         const int nn = n0 + n; const int drow = gu ? (((nn >> 7) << 8) + which * 128 + (nn & 127)) : nn;
;         *(u32x4*)(WT + (size_t)drow * ldk + koff + k0 + 8 * c) = o; }
;     LDS_WAIT();
	ds_write2_b32 v0, v54, v55 offset1:1
	v_add_u32_e32 v0, 0x34d8, v73
	ds_write2_b32 v0, v56, v57 offset1:1
	v_add_u32_e32 v0, 0x38e0, v73
	s_waitcnt vmcnt(1)
	ds_write2_b32 v0, v58, v59 offset1:1
	v_add_u32_e32 v0, 0x38e8, v73
	ds_write2_b32 v0, v60, v61 offset1:1
	v_add_u32_e32 v0, 0x3cf0, v73
	s_waitcnt vmcnt(0)
	ds_write2_b32 v0, v62, v63 offset1:1
	v_add_u32_e32 v0, 0x3cf8, v73
	ds_write2_b32 v0, v64, v65 offset1:1
	s_waitcnt lgkmcnt(0)
	ds_read2_b32 v[2:3], v93 offset1:65
	s_waitcnt lgkmcnt(0)
	v_cvt_pk_bf16_f32 v2, v2, v3
	ds_read2_b32 v[4:5], v93 offset0:130 offset1:195
	v_add_u32_e32 v0, 0x400, v93
	s_waitcnt lgkmcnt(0)
	v_cvt_pk_bf16_f32 v3, v4, v5
	ds_read2_b32 v[4:5], v0 offset0:4 offset1:69
	s_waitcnt lgkmcnt(0)
	v_cvt_pk_bf16_f32 v4, v4, v5
	ds_read2_b32 v[6:7], v0 offset0:134 offset1:199
	s_waitcnt lgkmcnt(0)
	v_cvt_pk_bf16_f32 v5, v6, v7
	v_add_u32_e32 v6, v90, v130
	v_ashrrev_i32_e32 v7, 31, v6
	v_lshlrev_b64 v[6:7], 12, v[6:7]
	v_lshl_add_u64 v[6:7], v[8:9], 0, v[6:7]
	ds_read2_b32 v[10:11], v93 offset0:8 offset1:73
	global_store_dwordx4 v[6:7], v[2:5], off
	s_waitcnt lgkmcnt(0)
	s_nop 0
	v_cvt_pk_bf16_f32 v2, v10, v11
	ds_read2_b32 v[4:5], v93 offset0:138 offset1:203
	s_waitcnt lgkmcnt(0)
	v_cvt_pk_bf16_f32 v3, v4, v5
	ds_read2_b32 v[4:5], v0 offset0:12 offset1:77
	s_waitcnt lgkmcnt(0)
	v_cvt_pk_bf16_f32 v4, v4, v5
	ds_read2_b32 v[6:7], v0 offset0:142 offset1:207
	s_waitcnt lgkmcnt(0)
	v_cvt_pk_bf16_f32 v5, v6, v7
	v_add_u32_e32 v6, v90, v129
	v_ashrrev_i32_e32 v7, 31, v6
	v_lshlrev_b64 v[6:7], 12, v[6:7]
	v_lshl_add_u64 v[6:7], v[8:9], 0, v[6:7]
	ds_read2_b32 v[10:11], v93 offset0:16 offset1:81
	global_store_dwordx4 v[6:7], v[2:5], off
	s_waitcnt lgkmcnt(0)
	s_nop 0
	v_cvt_pk_bf16_f32 v2, v10, v11
	ds_read2_b32 v[4:5], v93 offset0:146 offset1:211
	s_waitcnt lgkmcnt(0)
	v_cvt_pk_bf16_f32 v3, v4, v5
	ds_read2_b32 v[4:5], v0 offset0:20 offset1:85
	s_waitcnt lgkmcnt(0)
	v_cvt_pk_bf16_f32 v4, v4, v5
	ds_read2_b32 v[6:7], v0 offset0:150 offset1:215
	s_waitcnt lgkmcnt(0)
	v_cvt_pk_bf16_f32 v5, v6, v7
	v_add_u32_e32 v6, v90, v128
	v_ashrrev_i32_e32 v7, 31, v6
	v_lshlrev_b64 v[6:7], 12, v[6:7]
	v_lshl_add_u64 v[6:7], v[8:9], 0, v[6:7]
	ds_read2_b32 v[10:11], v93 offset0:24 offset1:89
	global_store_dwordx4 v[6:7], v[2:5], off
	s_waitcnt lgkmcnt(0)
	s_nop 0
	v_cvt_pk_bf16_f32 v2, v10, v11
	ds_read2_b32 v[4:5], v93 offset0:154 offset1:219
	s_waitcnt lgkmcnt(0)
	v_cvt_pk_bf16_f32 v3, v4, v5
	ds_read2_b32 v[4:5], v0 offset0:28 offset1:93
	s_waitcnt lgkmcnt(0)
	v_cvt_pk_bf16_f32 v4, v4, v5
	ds_read2_b32 v[6:7], v0 offset0:158 offset1:223
	s_waitcnt lgkmcnt(0)
	v_cvt_pk_bf16_f32 v5, v6, v7
	v_add_u32_e32 v6, v90, v127
	v_ashrrev_i32_e32 v7, 31, v6
	v_lshlrev_b64 v[6:7], 12, v[6:7]
	v_lshl_add_u64 v[6:7], v[8:9], 0, v[6:7]
	ds_read2_b32 v[10:11], v93 offset0:32 offset1:97
	global_store_dwordx4 v[6:7], v[2:5], off
	s_waitcnt lgkmcnt(0)
	s_nop 0
	v_cvt_pk_bf16_f32 v2, v10, v11
	ds_read2_b32 v[4:5], v93 offset0:162 offset1:227
	s_waitcnt lgkmcnt(0)
	v_cvt_pk_bf16_f32 v3, v4, v5
	ds_read2_b32 v[4:5], v0 offset0:36 offset1:101
	s_waitcnt lgkmcnt(0)
	v_cvt_pk_bf16_f32 v4, v4, v5
	ds_read2_b32 v[6:7], v0 offset0:166 offset1:231
	s_waitcnt lgkmcnt(0)
	v_cvt_pk_bf16_f32 v5, v6, v7
	v_add_u32_e32 v6, v90, v126
	v_ashrrev_i32_e32 v7, 31, v6
	v_lshlrev_b64 v[6:7], 12, v[6:7]
	v_lshl_add_u64 v[6:7], v[8:9], 0, v[6:7]
	ds_read2_b32 v[10:11], v93 offset0:40 offset1:105
	global_store_dwordx4 v[6:7], v[2:5], off
	s_waitcnt lgkmcnt(0)
	s_nop 0
	v_cvt_pk_bf16_f32 v2, v10, v11
	ds_read2_b32 v[4:5], v93 offset0:170 offset1:235
	s_waitcnt lgkmcnt(0)
	v_cvt_pk_bf16_f32 v3, v4, v5
	ds_read2_b32 v[4:5], v0 offset0:44 offset1:109
	s_waitcnt lgkmcnt(0)
	v_cvt_pk_bf16_f32 v4, v4, v5
	ds_read2_b32 v[6:7], v0 offset0:174 offset1:239
	s_waitcnt lgkmcnt(0)
	v_cvt_pk_bf16_f32 v5, v6, v7
	v_add_u32_e32 v6, v90, v125
	v_ashrrev_i32_e32 v7, 31, v6
	v_lshlrev_b64 v[6:7], 12, v[6:7]
	v_lshl_add_u64 v[6:7], v[8:9], 0, v[6:7]
	ds_read2_b32 v[10:11], v93 offset0:48 offset1:113
	global_store_dwordx4 v[6:7], v[2:5], off
	s_waitcnt lgkmcnt(0)
	s_nop 0
	v_cvt_pk_bf16_f32 v2, v10, v11
	ds_read2_b32 v[4:5], v93 offset0:178 offset1:243
	s_waitcnt lgkmcnt(0)
	v_cvt_pk_bf16_f32 v3, v4, v5
	ds_read2_b32 v[4:5], v0 offset0:52 offset1:117
	s_waitcnt lgkmcnt(0)
	v_cvt_pk_bf16_f32 v4, v4, v5
	ds_read2_b32 v[6:7], v0 offset0:182 offset1:247
	s_waitcnt lgkmcnt(0)
	v_cvt_pk_bf16_f32 v5, v6, v7
	v_add_u32_e32 v6, v90, v124
	v_ashrrev_i32_e32 v7, 31, v6
	v_lshlrev_b64 v[6:7], 12, v[6:7]
	v_lshl_add_u64 v[6:7], v[8:9], 0, v[6:7]
	ds_read2_b32 v[10:11], v93 offset0:56 offset1:121
	global_store_dwordx4 v[6:7], v[2:5], off
	s_waitcnt lgkmcnt(0)
	s_nop 0
	v_cvt_pk_bf16_f32 v2, v10, v11
	ds_read2_b32 v[4:5], v93 offset0:186 offset1:251
	s_waitcnt lgkmcnt(0)
	v_cvt_pk_bf16_f32 v3, v4, v5
	ds_read2_b32 v[4:5], v0 offset0:60 offset1:125
	s_waitcnt lgkmcnt(0)
	v_cvt_pk_bf16_f32 v4, v4, v5
	ds_read2_b32 v[6:7], v0 offset0:190 offset1:255
	s_waitcnt lgkmcnt(0)
	v_cvt_pk_bf16_f32 v5, v6, v7
	v_add_u32_e32 v6, v90, v122
	v_ashrrev_i32_e32 v7, 31, v6
	v_lshlrev_b64 v[6:7], 12, v[6:7]
	v_lshl_add_u64 v[6:7], v[8:9], 0, v[6:7]
	global_store_dwordx4 v[6:7], v[2:5], off
	s_waitcnt lgkmcnt(0)

; DI void tr_item(const float* W, int N, const float* scale, bf16_t* WT, int ldk, int koff, int gu, int which, float* scr, int item, int lane) {
;     const int nblk = N >> 6, kb = item / nblk, nb = item - kb * nblk, k0 = 64 * kb, n0 = 64 * nb;
;     const int lr = lane >> 4, lc = (lane & 15) * 4;
;     f32x4 v[16];
; #pragma unroll
;     for (int i = 0; i < 16; ++i) v[i] = *(const f32x4*)(W + (size_t)(k0 + 4 * i + lr) * N + n0 + lc);
; #pragma unroll
;     for (int i = 0; i < 16; ++i) { const int kk = 4 * i + lr; const float sc = scale ? scale[k0 + kk] : 1.f; float* d = scr + kk * 65 + lc;
;         d[0] = v[i].x * sc; d[1] = v[i].y * sc; d[2] = v[i].z * sc; d[3] = v[i].w * sc; }
; DI void conv_phase(PP P, int l, unsigned char* lds, int G, int cid) {
;     ...
;         if (r < I4) { tr_item(P->in[21] + (size_t)l * 1024 * DM, DM, nullptr, (bf16_t*)(ws + WS_WM), 2048, 1024, 0, 0, scr, r, lane); continue; } r -= I4;
.LBB0_450:
	s_andn2_saveexec_b64 s[12:13], s[72:73]
	s_cbranch_execz .LBB0_452
	s_load_dwordx2 s[4:5], s[0:1], 0xa8
	v_lshlrev_b32_e32 v0, 6, v132
	v_mov_b32_e32 v2, 0x3800
	v_and_b32_e32 v0, 0xfffff800, v0
	v_lshl_add_u32 v2, v113, 1, v2
	v_sub_u32_e32 v0, v114, v0
	v_and_b32_e32 v64, 0xffffffc0, v2
	s_waitcnt lgkmcnt(0)
	s_add_u32 s4, s4, s58
	v_add_u32_e32 v2, 0xfffb4000, v0
	s_addc_u32 s5, s5, s59
	v_ashrrev_i32_e32 v3, 31, v2
	v_or_b32_e32 v6, v64, v70
	v_lshl_add_u64 v[4:5], v[2:3], 2, s[4:5]
	v_lshlrev_b32_e32 v0, 2, v72
	v_lshl_add_u64 v[4:5], v[4:5], 0, v[0:1]
	v_lshlrev_b32_e32 v0, 11, v6
	v_lshl_add_u64 v[88:89], v[0:1], 2, v[4:5]
	v_add_co_u32_e32 v8, vcc, s81, v88
	s_mov_b32 s4, 0x28000
	s_nop 0
	v_addc_co_u32_e32 v9, vcc, 0, v89, vcc
	v_add_co_u32_e32 v12, vcc, s57, v88
	global_load_dwordx4 v[4:7], v[88:89], off nt
	s_nop 0
	global_load_dwordx4 v[8:11], v[8:9], off nt
	v_addc_co_u32_e32 v13, vcc, 0, v89, vcc
	v_add_co_u32_e32 v16, vcc, s76, v88
	v_add_u32_e32 v0, 0x410, v73
	s_nop 0
	v_addc_co_u32_e32 v17, vcc, 0, v89, vcc
	global_load_dwordx4 v[12:15], v[12:13], off nt
	s_nop 0
	global_load_dwordx4 v[16:19], v[16:17], off nt
	v_add_co_u32_e32 v20, vcc, s82, v88
	v_mov_b32_e32 v65, v1
	s_nop 0
	v_addc_co_u32_e32 v21, vcc, 0, v89, vcc
	v_add_co_u32_e32 v24, vcc, s4, v88
	s_mov_b32 s4, 0x30000
	s_nop 0
	v_addc_co_u32_e32 v25, vcc, 0, v89, vcc
	global_load_dwordx4 v[20:23], v[20:21], off nt
	s_nop 0
	global_load_dwordx4 v[24:27], v[24:25], off nt
	v_add_co_u32_e32 v28, vcc, s4, v88
	s_mov_b32 s4, 0x38000
	s_nop 0
	v_addc_co_u32_e32 v29, vcc, 0, v89, vcc
	v_add_co_u32_e32 v32, vcc, s4, v88
	s_mov_b32 s4, 0x48000
	s_nop 0
	v_addc_co_u32_e32 v33, vcc, 0, v89, vcc
	global_load_dwordx4 v[28:31], v[28:29], off nt
	s_nop 0
	global_load_dwordx4 v[32:35], v[32:33], off nt
	v_add_co_u32_e32 v36, vcc, s75, v88
	s_nop 1
	v_addc_co_u32_e32 v37, vcc, 0, v89, vcc
	v_add_co_u32_e32 v40, vcc, s4, v88
	s_mov_b32 s4, 0x50000
	s_nop 0
	v_addc_co_u32_e32 v41, vcc, 0, v89, vcc
	global_load_dwordx4 v[36:39], v[36:37], off nt
	s_nop 0
	global_load_dwordx4 v[40:43], v[40:41], off nt
	v_add_co_u32_e32 v44, vcc, s4, v88
	s_mov_b32 s4, 0x58000
	s_nop 0
	v_addc_co_u32_e32 v45, vcc, 0, v89, vcc
	v_add_co_u32_e32 v48, vcc, s4, v88
	s_mov_b32 s4, 0x60000
	s_nop 0
	v_addc_co_u32_e32 v49, vcc, 0, v89, vcc
	global_load_dwordx4 v[44:47], v[44:45], off nt
	s_nop 0
	global_load_dwordx4 v[48:51], v[48:49], off nt
	v_add_co_u32_e32 v52, vcc, s4, v88
	s_mov_b32 s4, 0x68000
	s_nop 0
	v_addc_co_u32_e32 v53, vcc, 0, v89, vcc
	global_load_dwordx4 v[52:55], v[52:53], off nt
	v_add_co_u32_e32 v56, vcc, s4, v88
	s_mov_b32 s4, 0x70000
	s_nop 0
	v_addc_co_u32_e32 v57, vcc, 0, v89, vcc
	global_load_dwordx4 v[56:59], v[56:57], off nt
	v_add_co_u32_e32 v60, vcc, s4, v88
	s_mov_b32 s4, 0x78000
	s_nop 0
	v_addc_co_u32_e32 v61, vcc, 0, v89, vcc
	global_load_dwordx4 v[60:63], v[60:61], off nt
	v_add_co_u32_e32 v88, vcc, s4, v88
	s_mov_b32 s4, 0x4c000
	s_nop 0
	v_addc_co_u32_e32 v89, vcc, 0, v89, vcc
	global_load_dwordx4 v[88:91], v[88:89], off nt
	s_waitcnt vmcnt(15)
	ds_write2_b32 v73, v4, v5 offset1:1
	ds_write2_b32 v73, v6, v7 offset0:2 offset1:3
	s_waitcnt vmcnt(14)
	ds_write2_b32 v0, v8, v9 offset1:1
	v_add_u32_e32 v0, 0x418, v73
	ds_write2_b32 v0, v10, v11 offset1:1
	v_add_u32_e32 v0, 0x820, v73
	v_lshl_add_u64 v[10:11], v[64:65], 1, v[82:83]
	s_waitcnt vmcnt(13)
	ds_write2_b32 v0, v12, v13 offset1:1
	v_add_u32_e32 v0, 0x828, v73
	ds_write2_b32 v0, v14, v15 offset1:1
	v_add_u32_e32 v0, 0xc30, v73
	s_waitcnt vmcnt(12)
	ds_write2_b32 v0, v16, v17 offset1:1
	v_add_u32_e32 v0, 0xc38, v73
	ds_write2_b32 v0, v18, v19 offset1:1
	v_add_u32_e32 v0, 0x1040, v73
	s_waitcnt vmcnt(11)
	ds_write2_b32 v0, v20, v21 offset1:1
	v_add_u32_e32 v0, 0x1048, v73
	ds_write2_b32 v0, v22, v23 offset1:1
	v_add_u32_e32 v0, 0x1450, v73
	s_waitcnt vmcnt(10)
	ds_write2_b32 v0, v24, v25 offset1:1
	v_add_u32_e32 v0, 0x1458, v73
	ds_write2_b32 v0, v26, v27 offset1:1
	v_add_u32_e32 v0, 0x1860, v73
	s_waitcnt vmcnt(9)
	ds_write2_b32 v0, v28, v29 offset1:1
	v_add_u32_e32 v0, 0x1868, v73
	ds_write2_b32 v0, v30, v31 offset1:1
	v_add_u32_e32 v0, 0x1c70, v73
	s_waitcnt vmcnt(8)
	ds_write2_b32 v0, v32, v33 offset1:1
	v_add_u32_e32 v0, 0x1c78, v73
	ds_write2_b32 v0, v34, v35 offset1:1
	v_add_u32_e32 v0, 0x2080, v73
	s_waitcnt vmcnt(7)
	ds_write2_b32 v0, v36, v37 offset1:1
	v_add_u32_e32 v0, 0x2088, v73
	ds_write2_b32 v0, v38, v39 offset1:1
	v_add_u32_e32 v0, 0x2490, v73
	s_waitcnt vmcnt(6)
	ds_write2_b32 v0, v40, v41 offset1:1
	v_add_u32_e32 v0, 0x2498, v73
	ds_write2_b32 v0, v42, v43 offset1:1
	v_add_u32_e32 v0, 0x28a0, v73
	s_waitcnt vmcnt(5)
	ds_write2_b32 v0, v44, v45 offset1:1
	v_add_u32_e32 v0, 0x28a8, v73
	ds_write2_b32 v0, v46, v47 offset1:1
	v_add_u32_e32 v0, 0x2cb0, v73
	s_waitcnt vmcnt(4)
	ds_write2_b32 v0, v48, v49 offset1:1
	v_add_u32_e32 v0, 0x2cb8, v73
	ds_write2_b32 v0, v50, v51 offset1:1
	v_add_u32_e32 v0, 0x30c0, v73
	s_waitcnt vmcnt(3)
	ds_write2_b32 v0, v52, v53 offset1:1
	v_add_u32_e32 v0, 0x30c8, v73
	ds_write2_b32 v0, v54, v55 offset1:1
	v_add_u32_e32 v0, 0x34d0, v73
	s_waitcnt vmcnt(2)
; DI unsigned cvt_pk_bf16(float lo, float hi) { unsigned r; asm volatile("v_cvt_pk_bf16_f32 %0, %1, %2" : "=v"(r) : "v"(lo), "v"(hi)); return r; }
; #define LDS_WAIT() asm volatile("s_waitcnt lgkmcnt(0)" ::: "memory")
; DI void tr_item(const float* W, int N, const float* scale, bf16_t* WT, int ldk, int koff, int gu, int which, float* scr, int item, int lane) {
;     ...
;     LDS_WAIT();
;     const int c = lane & 7;
; #pragma unroll
;     for (int j = 0; j < 8; ++j) { const int n = (lane >> 3) + 8 * j; const float* s = scr + (8 * c) * 65 + n;
;         u32x4 o; o.x = cvt_pk_bf16(s[0 * 65], s[1 * 65]); o.y = cvt_pk_bf16(s[2 * 65], s[3 * 65]); o.z = cvt_pk_bf16(s[4 * 65], s[5 * 65]); o.w = cvt_pk_bf16(s[6 * 65], s[7 * 65]);
;         const int nn = n0 + n; const int drow = gu ? (((nn >> 7) << 8) + which * 128 + (nn & 127)) : nn;
;         *(u32x4*)(WT + (size_t)drow * ldk + koff + k0 + 8 * c) = o; }
;     LDS_WAIT();
	ds_write2_b32 v0, v56, v57 offset1:1
	v_add_u32_e32 v0, 0x34d8, v73
	ds_write2_b32 v0, v58, v59 offset1:1
	v_add_u32_e32 v0, 0x38e0, v73
	s_waitcnt vmcnt(1)
	ds_write2_b32 v0, v60, v61 offset1:1
	v_add_u32_e32 v0, 0x38e8, v73
	ds_write2_b32 v0, v62, v63 offset1:1
	v_add_u32_e32 v0, 0x3cf0, v73
	s_waitcnt vmcnt(0)
	ds_write2_b32 v0, v88, v89 offset1:1
	v_add_u32_e32 v0, 0x3cf8, v73
	ds_write2_b32 v0, v90, v91 offset1:1
	s_waitcnt lgkmcnt(0)
	ds_read2_b32 v[4:5], v93 offset1:65
	s_waitcnt lgkmcnt(0)
	v_cvt_pk_bf16_f32 v4, v4, v5
	ds_read2_b32 v[6:7], v93 offset0:130 offset1:195
	v_add_u32_e32 v0, 0x400, v93
	s_waitcnt lgkmcnt(0)
	v_cvt_pk_bf16_f32 v5, v6, v7
	ds_read2_b32 v[6:7], v0 offset0:4 offset1:69
	s_waitcnt lgkmcnt(0)
	v_cvt_pk_bf16_f32 v6, v6, v7
	ds_read2_b32 v[8:9], v0 offset0:134 offset1:199
	s_waitcnt lgkmcnt(0)
	v_cvt_pk_bf16_f32 v7, v8, v9
	v_add3_u32 v8, v2, v139, s4
	v_ashrrev_i32_e32 v9, 31, v8
	v_lshlrev_b64 v[8:9], 12, v[8:9]
	v_lshl_add_u64 v[8:9], v[10:11], 0, v[8:9]
	ds_read2_b32 v[12:13], v93 offset0:8 offset1:73
	global_store_dwordx4 v[8:9], v[4:7], off
	s_waitcnt lgkmcnt(0)
	s_nop 0
	v_cvt_pk_bf16_f32 v4, v12, v13
	ds_read2_b32 v[6:7], v93 offset0:138 offset1:203
	s_waitcnt lgkmcnt(0)
	v_cvt_pk_bf16_f32 v5, v6, v7
	ds_read2_b32 v[6:7], v0 offset0:12 offset1:77
	s_waitcnt lgkmcnt(0)
	v_cvt_pk_bf16_f32 v6, v6, v7
	ds_read2_b32 v[8:9], v0 offset0:142 offset1:207
	s_waitcnt lgkmcnt(0)
	v_cvt_pk_bf16_f32 v7, v8, v9
	v_add3_u32 v8, v2, v138, s4
	v_ashrrev_i32_e32 v9, 31, v8
	v_lshlrev_b64 v[8:9], 12, v[8:9]
	v_lshl_add_u64 v[8:9], v[10:11], 0, v[8:9]
	ds_read2_b32 v[12:13], v93 offset0:16 offset1:81
	global_store_dwordx4 v[8:9], v[4:7], off
	s_waitcnt lgkmcnt(0)
	s_nop 0
	v_cvt_pk_bf16_f32 v4, v12, v13
	ds_read2_b32 v[6:7], v93 offset0:146 offset1:211
	s_waitcnt lgkmcnt(0)
	v_cvt_pk_bf16_f32 v5, v6, v7
	ds_read2_b32 v[6:7], v0 offset0:20 offset1:85
	s_waitcnt lgkmcnt(0)
	v_cvt_pk_bf16_f32 v6, v6, v7
	ds_read2_b32 v[8:9], v0 offset0:150 offset1:215
	s_waitcnt lgkmcnt(0)
	v_cvt_pk_bf16_f32 v7, v8, v9
	v_add3_u32 v8, v2, v137, s4
	v_ashrrev_i32_e32 v9, 31, v8
	v_lshlrev_b64 v[8:9], 12, v[8:9]
	v_lshl_add_u64 v[8:9], v[10:11], 0, v[8:9]
	ds_read2_b32 v[12:13], v93 offset0:24 offset1:89
	global_store_dwordx4 v[8:9], v[4:7], off
	s_waitcnt lgkmcnt(0)
	s_nop 0
	v_cvt_pk_bf16_f32 v4, v12, v13
	ds_read2_b32 v[6:7], v93 offset0:154 offset1:219
	s_waitcnt lgkmcnt(0)
	v_cvt_pk_bf16_f32 v5, v6, v7
	ds_read2_b32 v[6:7], v0 offset0:28 offset1:93
	s_waitcnt lgkmcnt(0)
	v_cvt_pk_bf16_f32 v6, v6, v7
	ds_read2_b32 v[8:9], v0 offset0:158 offset1:223
	s_waitcnt lgkmcnt(0)
	v_cvt_pk_bf16_f32 v7, v8, v9
	v_add3_u32 v8, v2, v136, s4
	v_ashrrev_i32_e32 v9, 31, v8
	v_lshlrev_b64 v[8:9], 12, v[8:9]
	v_lshl_add_u64 v[8:9], v[10:11], 0, v[8:9]
	ds_read2_b32 v[12:13], v93 offset0:32 offset1:97
	global_store_dwordx4 v[8:9], v[4:7], off
	s_waitcnt lgkmcnt(0)
	s_nop 0
	v_cvt_pk_bf16_f32 v4, v12, v13
	ds_read2_b32 v[6:7], v93 offset0:162 offset1:227
	s_waitcnt lgkmcnt(0)
	v_cvt_pk_bf16_f32 v5, v6, v7
	ds_read2_b32 v[6:7], v0 offset0:36 offset1:101
	s_waitcnt lgkmcnt(0)
	v_cvt_pk_bf16_f32 v6, v6, v7
	ds_read2_b32 v[8:9], v0 offset0:166 offset1:231
	s_waitcnt lgkmcnt(0)
	v_cvt_pk_bf16_f32 v7, v8, v9
	v_add3_u32 v8, v2, v135, s4
	v_ashrrev_i32_e32 v9, 31, v8
	v_lshlrev_b64 v[8:9], 12, v[8:9]
	v_lshl_add_u64 v[8:9], v[10:11], 0, v[8:9]
	ds_read2_b32 v[12:13], v93 offset0:40 offset1:105
	global_store_dwordx4 v[8:9], v[4:7], off
	s_waitcnt lgkmcnt(0)
	s_nop 0
	v_cvt_pk_bf16_f32 v4, v12, v13
	ds_read2_b32 v[6:7], v93 offset0:170 offset1:235
	s_waitcnt lgkmcnt(0)
	v_cvt_pk_bf16_f32 v5, v6, v7
	ds_read2_b32 v[6:7], v0 offset0:44 offset1:109
	s_waitcnt lgkmcnt(0)
	v_cvt_pk_bf16_f32 v6, v6, v7
	ds_read2_b32 v[8:9], v0 offset0:174 offset1:239
	s_waitcnt lgkmcnt(0)
	v_cvt_pk_bf16_f32 v7, v8, v9
	v_add3_u32 v8, v2, v134, s4
	v_ashrrev_i32_e32 v9, 31, v8
	v_lshlrev_b64 v[8:9], 12, v[8:9]
	v_lshl_add_u64 v[8:9], v[10:11], 0, v[8:9]
	ds_read2_b32 v[12:13], v93 offset0:48 offset1:113
	global_store_dwordx4 v[8:9], v[4:7], off
	s_waitcnt lgkmcnt(0)
	s_nop 0
	v_cvt_pk_bf16_f32 v4, v12, v13
	ds_read2_b32 v[6:7], v93 offset0:178 offset1:243
	s_waitcnt lgkmcnt(0)
	v_cvt_pk_bf16_f32 v5, v6, v7
	ds_read2_b32 v[6:7], v0 offset0:52 offset1:117
	s_waitcnt lgkmcnt(0)
	v_cvt_pk_bf16_f32 v6, v6, v7
	ds_read2_b32 v[8:9], v0 offset0:182 offset1:247
	s_waitcnt lgkmcnt(0)
	v_cvt_pk_bf16_f32 v7, v8, v9
	v_add3_u32 v8, v2, v133, s4
	v_ashrrev_i32_e32 v9, 31, v8
	v_lshlrev_b64 v[8:9], 12, v[8:9]
	v_add3_u32 v2, v2, v131, s4
	v_lshl_add_u64 v[8:9], v[10:11], 0, v[8:9]
	v_ashrrev_i32_e32 v3, 31, v2
	ds_read2_b32 v[12:13], v93 offset0:56 offset1:121
	global_store_dwordx4 v[8:9], v[4:7], off
	v_lshlrev_b64 v[2:3], 12, v[2:3]
	v_lshl_add_u64 v[2:3], v[10:11], 0, v[2:3]
	s_waitcnt lgkmcnt(0)
	v_cvt_pk_bf16_f32 v4, v12, v13
	ds_read2_b32 v[6:7], v93 offset0:186 offset1:251
	s_waitcnt lgkmcnt(0)
	v_cvt_pk_bf16_f32 v5, v6, v7
	ds_read2_b32 v[6:7], v0 offset0:60 offset1:125
	s_waitcnt lgkmcnt(0)
	v_cvt_pk_bf16_f32 v6, v6, v7
	ds_read2_b32 v[8:9], v0 offset0:190 offset1:255
	s_waitcnt lgkmcnt(0)
	v_cvt_pk_bf16_f32 v7, v8, v9
	global_store_dwordx4 v[2:3], v[4:7], off
	s_waitcnt lgkmcnt(0)

; DI void tr_item(const float* W, int N, const float* scale, bf16_t* WT, int ldk, int koff, int gu, int which, float* scr, int item, int lane) {
;     const int nblk = N >> 6, kb = item / nblk, nb = item - kb * nblk, k0 = 64 * kb, n0 = 64 * nb;
;     const int lr = lane >> 4, lc = (lane & 15) * 4;
;     f32x4 v[16];
; #pragma unroll
;     for (int i = 0; i < 16; ++i) v[i] = *(const f32x4*)(W + (size_t)(k0 + 4 * i + lr) * N + n0 + lc);
; #pragma unroll
;     for (int i = 0; i < 16; ++i) { const int kk = 4 * i + lr; const float sc = scale ? scale[k0 + kk] : 1.f; float* d = scr + kk * 65 + lc;
;         d[0] = v[i].x * sc; d[1] = v[i].y * sc; d[2] = v[i].z * sc; d[3] = v[i].w * sc; }
; DI void conv_phase(PP P, int l, unsigned char* lds, int G, int cid) {
;     ...
;         if (r < I3) { tr_item(P->in[20] + (size_t)l * 1024 * DM, DM, nullptr, (bf16_t*)(ws + WS_WM), 2048, 0, 0, 0, scr, r, lane); continue; } r -= I3;
.LBB0_453:
	s_andn2_saveexec_b64 s[12:13], s[16:17]
	s_cbranch_execz .LBB0_455
	s_load_dwordx2 s[4:5], s[0:1], 0xa0
	v_lshlrev_b32_e32 v0, 6, v141
	v_mov_b32_e32 v2, 0x3c00
	v_and_b32_e32 v0, 0xfffff800, v0
	v_lshl_add_u32 v2, v113, 1, v2
	v_sub_u32_e32 v0, v114, v0
	v_and_b32_e32 v64, 0xffffffc0, v2
	s_waitcnt lgkmcnt(0)
	s_add_u32 s4, s4, s58
	v_add_u32_e32 v2, 0xfffbc000, v0
	s_addc_u32 s5, s5, s59
	v_ashrrev_i32_e32 v3, 31, v2
	v_or_b32_e32 v6, v64, v70
	v_lshl_add_u64 v[4:5], v[2:3], 2, s[4:5]
	v_lshlrev_b32_e32 v0, 2, v72
	v_lshl_add_u64 v[4:5], v[4:5], 0, v[0:1]
	v_lshlrev_b32_e32 v0, 11, v6
	v_lshl_add_u64 v[88:89], v[0:1], 2, v[4:5]
	v_add_co_u32_e32 v8, vcc, s81, v88
	s_mov_b32 s4, 0x28000
	s_nop 0
	v_addc_co_u32_e32 v9, vcc, 0, v89, vcc
	v_add_co_u32_e32 v12, vcc, s57, v88
	global_load_dwordx4 v[4:7], v[88:89], off nt
	s_nop 0
	global_load_dwordx4 v[8:11], v[8:9], off nt
	v_addc_co_u32_e32 v13, vcc, 0, v89, vcc
	v_add_co_u32_e32 v16, vcc, s76, v88
	v_add_u32_e32 v0, 0x410, v73
	s_nop 0
	v_addc_co_u32_e32 v17, vcc, 0, v89, vcc
	global_load_dwordx4 v[12:15], v[12:13], off nt
	s_nop 0
	global_load_dwordx4 v[16:19], v[16:17], off nt
	v_add_co_u32_e32 v20, vcc, s82, v88
	v_mov_b32_e32 v65, v1
	s_nop 0
	v_addc_co_u32_e32 v21, vcc, 0, v89, vcc
	v_add_co_u32_e32 v24, vcc, s4, v88
	s_mov_b32 s4, 0x30000
	s_nop 0
	v_addc_co_u32_e32 v25, vcc, 0, v89, vcc
	global_load_dwordx4 v[20:23], v[20:21], off nt
	s_nop 0
	global_load_dwordx4 v[24:27], v[24:25], off nt
	v_add_co_u32_e32 v28, vcc, s4, v88
	s_mov_b32 s4, 0x38000
	s_nop 0
	v_addc_co_u32_e32 v29, vcc, 0, v89, vcc
	v_add_co_u32_e32 v32, vcc, s4, v88
	s_mov_b32 s4, 0x48000
	s_nop 0
	v_addc_co_u32_e32 v33, vcc, 0, v89, vcc
	global_load_dwordx4 v[28:31], v[28:29], off nt
	s_nop 0
	global_load_dwordx4 v[32:35], v[32:33], off nt
	v_add_co_u32_e32 v36, vcc, s75, v88
	s_nop 1
	v_addc_co_u32_e32 v37, vcc, 0, v89, vcc
	v_add_co_u32_e32 v40, vcc, s4, v88
	s_mov_b32 s4, 0x50000
	s_nop 0
	v_addc_co_u32_e32 v41, vcc, 0, v89, vcc
	global_load_dwordx4 v[36:39], v[36:37], off nt
	s_nop 0
	global_load_dwordx4 v[40:43], v[40:41], off nt
	v_add_co_u32_e32 v44, vcc, s4, v88
	s_mov_b32 s4, 0x58000
	s_nop 0
	v_addc_co_u32_e32 v45, vcc, 0, v89, vcc
	v_add_co_u32_e32 v48, vcc, s4, v88
	s_mov_b32 s4, 0x60000
	s_nop 0
	v_addc_co_u32_e32 v49, vcc, 0, v89, vcc
	global_load_dwordx4 v[44:47], v[44:45], off nt
	s_nop 0
	global_load_dwordx4 v[48:51], v[48:49], off nt
	v_add_co_u32_e32 v52, vcc, s4, v88
	s_mov_b32 s4, 0x68000
	s_nop 0
	v_addc_co_u32_e32 v53, vcc, 0, v89, vcc
	global_load_dwordx4 v[52:55], v[52:53], off nt
	v_add_co_u32_e32 v56, vcc, s4, v88
	s_mov_b32 s4, 0x70000
	s_nop 0
	v_addc_co_u32_e32 v57, vcc, 0, v89, vcc
	global_load_dwordx4 v[56:59], v[56:57], off nt
	v_add_co_u32_e32 v60, vcc, s4, v88
	s_mov_b32 s4, 0x78000
	s_nop 0
	v_addc_co_u32_e32 v61, vcc, 0, v89, vcc
	global_load_dwordx4 v[60:63], v[60:61], off nt
	v_add_co_u32_e32 v88, vcc, s4, v88
	s_mov_b32 s4, 0x44000
	s_nop 0
	v_addc_co_u32_e32 v89, vcc, 0, v89, vcc
	global_load_dwordx4 v[88:91], v[88:89], off nt
	s_waitcnt vmcnt(15)
	ds_write2_b32 v73, v4, v5 offset1:1
	ds_write2_b32 v73, v6, v7 offset0:2 offset1:3
	s_waitcnt vmcnt(14)
	ds_write2_b32 v0, v8, v9 offset1:1
	v_add_u32_e32 v0, 0x418, v73
	ds_write2_b32 v0, v10, v11 offset1:1
	v_add_u32_e32 v0, 0x820, v73
	v_lshl_add_u64 v[10:11], v[64:65], 1, v[84:85]
	s_waitcnt vmcnt(13)
	ds_write2_b32 v0, v12, v13 offset1:1
	v_add_u32_e32 v0, 0x828, v73
	ds_write2_b32 v0, v14, v15 offset1:1
	v_add_u32_e32 v0, 0xc30, v73
	s_waitcnt vmcnt(12)
	ds_write2_b32 v0, v16, v17 offset1:1
	v_add_u32_e32 v0, 0xc38, v73
	ds_write2_b32 v0, v18, v19 offset1:1
	v_add_u32_e32 v0, 0x1040, v73
	s_waitcnt vmcnt(11)
	ds_write2_b32 v0, v20, v21 offset1:1
	v_add_u32_e32 v0, 0x1048, v73
	ds_write2_b32 v0, v22, v23 offset1:1
	v_add_u32_e32 v0, 0x1450, v73
	s_waitcnt vmcnt(10)
	ds_write2_b32 v0, v24, v25 offset1:1
	v_add_u32_e32 v0, 0x1458, v73
	ds_write2_b32 v0, v26, v27 offset1:1
	v_add_u32_e32 v0, 0x1860, v73
	s_waitcnt vmcnt(9)
	ds_write2_b32 v0, v28, v29 offset1:1
	v_add_u32_e32 v0, 0x1868, v73
	ds_write2_b32 v0, v30, v31 offset1:1
	v_add_u32_e32 v0, 0x1c70, v73
	s_waitcnt vmcnt(8)
	ds_write2_b32 v0, v32, v33 offset1:1
	v_add_u32_e32 v0, 0x1c78, v73
	ds_write2_b32 v0, v34, v35 offset1:1
	v_add_u32_e32 v0, 0x2080, v73
	s_waitcnt vmcnt(7)
	ds_write2_b32 v0, v36, v37 offset1:1
	v_add_u32_e32 v0, 0x2088, v73
	ds_write2_b32 v0, v38, v39 offset1:1
	v_add_u32_e32 v0, 0x2490, v73
	s_waitcnt vmcnt(6)
	ds_write2_b32 v0, v40, v41 offset1:1
	v_add_u32_e32 v0, 0x2498, v73
	ds_write2_b32 v0, v42, v43 offset1:1
	v_add_u32_e32 v0, 0x28a0, v73
	s_waitcnt vmcnt(5)
	ds_write2_b32 v0, v44, v45 offset1:1
	v_add_u32_e32 v0, 0x28a8, v73
	ds_write2_b32 v0, v46, v47 offset1:1
	v_add_u32_e32 v0, 0x2cb0, v73
	s_waitcnt vmcnt(4)
	ds_write2_b32 v0, v48, v49 offset1:1
	v_add_u32_e32 v0, 0x2cb8, v73
	ds_write2_b32 v0, v50, v51 offset1:1
	v_add_u32_e32 v0, 0x30c0, v73
	s_waitcnt vmcnt(3)
	ds_write2_b32 v0, v52, v53 offset1:1
	v_add_u32_e32 v0, 0x30c8, v73
	ds_write2_b32 v0, v54, v55 offset1:1
	v_add_u32_e32 v0, 0x34d0, v73
	s_waitcnt vmcnt(2)
; DI unsigned cvt_pk_bf16(float lo, float hi) { unsigned r; asm volatile("v_cvt_pk_bf16_f32 %0, %1, %2" : "=v"(r) : "v"(lo), "v"(hi)); return r; }
; #define LDS_WAIT() asm volatile("s_waitcnt lgkmcnt(0)" ::: "memory")
; DI void tr_item(const float* W, int N, const float* scale, bf16_t* WT, int ldk, int koff, int gu, int which, float* scr, int item, int lane) {
;     ...
;     LDS_WAIT();
;     const int c = lane & 7;
; #pragma unroll
;     for (int j = 0; j < 8; ++j) { const int n = (lane >> 3) + 8 * j; const float* s = scr + (8 * c) * 65 + n;
;         u32x4 o; o.x = cvt_pk_bf16(s[0 * 65], s[1 * 65]); o.y = cvt_pk_bf16(s[2 * 65], s[3 * 65]); o.z = cvt_pk_bf16(s[4 * 65], s[5 * 65]); o.w = cvt_pk_bf16(s[6 * 65], s[7 * 65]);
;         const int nn = n0 + n; const int drow = gu ? (((nn >> 7) << 8) + which * 128 + (nn & 127)) : nn;
;         *(u32x4*)(WT + (size_t)drow * ldk + koff + k0 + 8 * c) = o; }
;     LDS_WAIT();
	ds_write2_b32 v0, v56, v57 offset1:1
	v_add_u32_e32 v0, 0x34d8, v73
	ds_write2_b32 v0, v58, v59 offset1:1
	v_add_u32_e32 v0, 0x38e0, v73
	s_waitcnt vmcnt(1)
	ds_write2_b32 v0, v60, v61 offset1:1
	v_add_u32_e32 v0, 0x38e8, v73
	ds_write2_b32 v0, v62, v63 offset1:1
	v_add_u32_e32 v0, 0x3cf0, v73
	s_waitcnt vmcnt(0)
	ds_write2_b32 v0, v88, v89 offset1:1
	v_add_u32_e32 v0, 0x3cf8, v73
	ds_write2_b32 v0, v90, v91 offset1:1
	s_waitcnt lgkmcnt(0)
	ds_read2_b32 v[4:5], v93 offset1:65
	s_waitcnt lgkmcnt(0)
	v_cvt_pk_bf16_f32 v4, v4, v5
	ds_read2_b32 v[6:7], v93 offset0:130 offset1:195
	v_add_u32_e32 v0, 0x400, v93
	s_waitcnt lgkmcnt(0)
	v_cvt_pk_bf16_f32 v5, v6, v7
	ds_read2_b32 v[6:7], v0 offset0:4 offset1:69
	s_waitcnt lgkmcnt(0)
	v_cvt_pk_bf16_f32 v6, v6, v7
	ds_read2_b32 v[8:9], v0 offset0:134 offset1:199
	s_waitcnt lgkmcnt(0)
	v_cvt_pk_bf16_f32 v7, v8, v9
	v_add3_u32 v8, v2, v148, s4
	v_ashrrev_i32_e32 v9, 31, v8
	v_lshlrev_b64 v[8:9], 12, v[8:9]
	v_lshl_add_u64 v[8:9], v[10:11], 0, v[8:9]
	ds_read2_b32 v[12:13], v93 offset0:8 offset1:73
	global_store_dwordx4 v[8:9], v[4:7], off
	s_waitcnt lgkmcnt(0)
	s_nop 0
	v_cvt_pk_bf16_f32 v4, v12, v13
	ds_read2_b32 v[6:7], v93 offset0:138 offset1:203
	s_waitcnt lgkmcnt(0)
	v_cvt_pk_bf16_f32 v5, v6, v7
	ds_read2_b32 v[6:7], v0 offset0:12 offset1:77
	s_waitcnt lgkmcnt(0)
	v_cvt_pk_bf16_f32 v6, v6, v7
	ds_read2_b32 v[8:9], v0 offset0:142 offset1:207
	s_waitcnt lgkmcnt(0)
	v_cvt_pk_bf16_f32 v7, v8, v9
	v_add3_u32 v8, v2, v147, s4
	v_ashrrev_i32_e32 v9, 31, v8
	v_lshlrev_b64 v[8:9], 12, v[8:9]
	v_lshl_add_u64 v[8:9], v[10:11], 0, v[8:9]
	ds_read2_b32 v[12:13], v93 offset0:16 offset1:81
	global_store_dwordx4 v[8:9], v[4:7], off
	s_waitcnt lgkmcnt(0)
	s_nop 0
	v_cvt_pk_bf16_f32 v4, v12, v13
	ds_read2_b32 v[6:7], v93 offset0:146 offset1:211
	s_waitcnt lgkmcnt(0)
	v_cvt_pk_bf16_f32 v5, v6, v7
	ds_read2_b32 v[6:7], v0 offset0:20 offset1:85
	s_waitcnt lgkmcnt(0)
	v_cvt_pk_bf16_f32 v6, v6, v7
	ds_read2_b32 v[8:9], v0 offset0:150 offset1:215
	s_waitcnt lgkmcnt(0)
	v_cvt_pk_bf16_f32 v7, v8, v9
	v_add3_u32 v8, v2, v146, s4
	v_ashrrev_i32_e32 v9, 31, v8
	v_lshlrev_b64 v[8:9], 12, v[8:9]
	v_lshl_add_u64 v[8:9], v[10:11], 0, v[8:9]
	ds_read2_b32 v[12:13], v93 offset0:24 offset1:89
	global_store_dwordx4 v[8:9], v[4:7], off
	s_waitcnt lgkmcnt(0)
	s_nop 0
	v_cvt_pk_bf16_f32 v4, v12, v13
	ds_read2_b32 v[6:7], v93 offset0:154 offset1:219
	s_waitcnt lgkmcnt(0)
	v_cvt_pk_bf16_f32 v5, v6, v7
	ds_read2_b32 v[6:7], v0 offset0:28 offset1:93
	s_waitcnt lgkmcnt(0)
	v_cvt_pk_bf16_f32 v6, v6, v7
	ds_read2_b32 v[8:9], v0 offset0:158 offset1:223
	s_waitcnt lgkmcnt(0)
	v_cvt_pk_bf16_f32 v7, v8, v9
	v_add3_u32 v8, v2, v145, s4
	v_ashrrev_i32_e32 v9, 31, v8
	v_lshlrev_b64 v[8:9], 12, v[8:9]
	v_lshl_add_u64 v[8:9], v[10:11], 0, v[8:9]
	ds_read2_b32 v[12:13], v93 offset0:32 offset1:97
	global_store_dwordx4 v[8:9], v[4:7], off
	s_waitcnt lgkmcnt(0)
	s_nop 0
	v_cvt_pk_bf16_f32 v4, v12, v13
	ds_read2_b32 v[6:7], v93 offset0:162 offset1:227
	s_waitcnt lgkmcnt(0)
	v_cvt_pk_bf16_f32 v5, v6, v7
	ds_read2_b32 v[6:7], v0 offset0:36 offset1:101
	s_waitcnt lgkmcnt(0)
	v_cvt_pk_bf16_f32 v6, v6, v7
	ds_read2_b32 v[8:9], v0 offset0:166 offset1:231
	s_waitcnt lgkmcnt(0)
	v_cvt_pk_bf16_f32 v7, v8, v9
	v_add3_u32 v8, v2, v144, s4
	v_ashrrev_i32_e32 v9, 31, v8
	v_lshlrev_b64 v[8:9], 12, v[8:9]
	v_lshl_add_u64 v[8:9], v[10:11], 0, v[8:9]
	ds_read2_b32 v[12:13], v93 offset0:40 offset1:105
	global_store_dwordx4 v[8:9], v[4:7], off
	s_waitcnt lgkmcnt(0)
	s_nop 0
	v_cvt_pk_bf16_f32 v4, v12, v13
	ds_read2_b32 v[6:7], v93 offset0:170 offset1:235
	s_waitcnt lgkmcnt(0)
	v_cvt_pk_bf16_f32 v5, v6, v7
	ds_read2_b32 v[6:7], v0 offset0:44 offset1:109
	s_waitcnt lgkmcnt(0)
	v_cvt_pk_bf16_f32 v6, v6, v7
	ds_read2_b32 v[8:9], v0 offset0:174 offset1:239
	s_waitcnt lgkmcnt(0)
	v_cvt_pk_bf16_f32 v7, v8, v9
	v_add3_u32 v8, v2, v143, s4
	v_ashrrev_i32_e32 v9, 31, v8
	v_lshlrev_b64 v[8:9], 12, v[8:9]
	v_lshl_add_u64 v[8:9], v[10:11], 0, v[8:9]
	ds_read2_b32 v[12:13], v93 offset0:48 offset1:113
	global_store_dwordx4 v[8:9], v[4:7], off
	s_waitcnt lgkmcnt(0)
	s_nop 0
	v_cvt_pk_bf16_f32 v4, v12, v13
	ds_read2_b32 v[6:7], v93 offset0:178 offset1:243
	s_waitcnt lgkmcnt(0)
	v_cvt_pk_bf16_f32 v5, v6, v7
	ds_read2_b32 v[6:7], v0 offset0:52 offset1:117
	s_waitcnt lgkmcnt(0)
	v_cvt_pk_bf16_f32 v6, v6, v7
	ds_read2_b32 v[8:9], v0 offset0:182 offset1:247
	s_waitcnt lgkmcnt(0)
	v_cvt_pk_bf16_f32 v7, v8, v9
	v_add3_u32 v8, v2, v142, s4
	v_ashrrev_i32_e32 v9, 31, v8
	v_lshlrev_b64 v[8:9], 12, v[8:9]
	v_add3_u32 v2, v2, v140, s4
	v_lshl_add_u64 v[8:9], v[10:11], 0, v[8:9]
	v_ashrrev_i32_e32 v3, 31, v2
	ds_read2_b32 v[12:13], v93 offset0:56 offset1:121
	global_store_dwordx4 v[8:9], v[4:7], off
	v_lshlrev_b64 v[2:3], 12, v[2:3]
	v_lshl_add_u64 v[2:3], v[10:11], 0, v[2:3]
	s_waitcnt lgkmcnt(0)
	v_cvt_pk_bf16_f32 v4, v12, v13
	ds_read2_b32 v[6:7], v93 offset0:186 offset1:251
	s_waitcnt lgkmcnt(0)
	v_cvt_pk_bf16_f32 v5, v6, v7
	ds_read2_b32 v[6:7], v0 offset0:60 offset1:125
	s_waitcnt lgkmcnt(0)
	v_cvt_pk_bf16_f32 v6, v6, v7
	ds_read2_b32 v[8:9], v0 offset0:190 offset1:255
	s_waitcnt lgkmcnt(0)
	v_cvt_pk_bf16_f32 v7, v8, v9
	global_store_dwordx4 v[2:3], v[4:7], off
	s_waitcnt lgkmcnt(0)

; DI void tr_item(const float* W, int N, const float* scale, bf16_t* WT, int ldk, int koff, int gu, int which, float* scr, int item, int lane) {
;     const int nblk = N >> 6, kb = item / nblk, nb = item - kb * nblk, k0 = 64 * kb, n0 = 64 * nb;
;     const int lr = lane >> 4, lc = (lane & 15) * 4;
;     f32x4 v[16];
; #pragma unroll
;     for (int i = 0; i < 16; ++i) v[i] = *(const f32x4*)(W + (size_t)(k0 + 4 * i + lr) * N + n0 + lc);
; #pragma unroll
;     for (int i = 0; i < 16; ++i) { const int kk = 4 * i + lr; const float sc = scale ? scale[k0 + kk] : 1.f; float* d = scr + kk * 65 + lc;
;         d[0] = v[i].x * sc; d[1] = v[i].y * sc; d[2] = v[i].z * sc; d[3] = v[i].w * sc; }
; DI void conv_phase(PP P, int l, unsigned char* lds, int G, int cid) {
;     ...
;         if (r < I2) { tr_item(P->in[11] + (size_t)l * 1024 * 1024, 1024, nullptr, (bf16_t*)(ws + WS_WGLU), 1024, 0, 0, 0, scr, r, lane); continue; } r -= I2;
.LBB0_456:
	s_andn2_saveexec_b64 s[12:13], s[14:15]
	s_cbranch_execz .LBB0_458
	s_load_dwordx2 s[4:5], s[0:1], 0x58
	v_lshlrev_b32_e32 v2, 6, v157
	v_bfe_u32 v158, v0, 4, 4
	v_and_b32_e32 v0, 0x3c00, v2
	v_sub_u32_e32 v0, v114, v0
	s_waitcnt lgkmcnt(0)
	s_add_u32 s4, s4, s60
	v_add_u32_e32 v2, 0xfffc0000, v0
	s_addc_u32 s5, s5, s61
	v_ashrrev_i32_e32 v3, 31, v2
	v_lshl_add_u64 v[4:5], v[2:3], 2, s[4:5]
	v_lshlrev_b32_e32 v0, 2, v72
	v_lshl_add_u64 v[4:5], v[4:5], 0, v[0:1]
	v_lshlrev_b32_e32 v0, 12, v70
	v_lshl_or_b32 v0, v158, 18, v0
	v_lshl_add_u64 v[64:65], v[4:5], 0, v[0:1]
	s_movk_i32 s4, 0x4000
	v_add_co_u32_e32 v8, vcc, s4, v64
	s_mov_b32 s4, 0xc000
	s_nop 0
	v_addc_co_u32_e32 v9, vcc, 0, v65, vcc
	v_add_co_u32_e32 v12, vcc, s81, v64
	global_load_dwordx4 v[4:7], v[64:65], off nt
	s_nop 0
	global_load_dwordx4 v[8:11], v[8:9], off nt
	v_addc_co_u32_e32 v13, vcc, 0, v65, vcc
	v_add_co_u32_e32 v16, vcc, s4, v64
	s_mov_b32 s4, 0x14000
	s_nop 0
	v_addc_co_u32_e32 v17, vcc, 0, v65, vcc
	global_load_dwordx4 v[12:15], v[12:13], off nt
	s_nop 0
	global_load_dwordx4 v[16:19], v[16:17], off nt
	v_add_co_u32_e32 v20, vcc, s57, v64
	v_add_u32_e32 v0, 0x410, v73
	s_nop 0
	v_addc_co_u32_e32 v21, vcc, 0, v65, vcc
	v_add_co_u32_e32 v24, vcc, s4, v64
	s_mov_b32 s4, 0x1c000
	s_nop 0
	v_addc_co_u32_e32 v25, vcc, 0, v65, vcc
	global_load_dwordx4 v[20:23], v[20:21], off nt
	s_nop 0
	global_load_dwordx4 v[24:27], v[24:25], off nt
	v_add_co_u32_e32 v28, vcc, s76, v64
	v_add_u32_e32 v3, 0x400, v93
	s_nop 0
	v_addc_co_u32_e32 v29, vcc, 0, v65, vcc
	v_add_co_u32_e32 v32, vcc, s4, v64
	s_mov_b32 s4, 0x24000
	s_nop 0
	v_addc_co_u32_e32 v33, vcc, 0, v65, vcc
	global_load_dwordx4 v[28:31], v[28:29], off nt
	s_nop 0
	global_load_dwordx4 v[32:35], v[32:33], off nt
	v_add_co_u32_e32 v36, vcc, s82, v64
	s_nop 1
	v_addc_co_u32_e32 v37, vcc, 0, v65, vcc
	v_add_co_u32_e32 v40, vcc, s4, v64
	s_mov_b32 s4, 0x28000
	s_nop 0
	v_addc_co_u32_e32 v41, vcc, 0, v65, vcc
	global_load_dwordx4 v[36:39], v[36:37], off nt
	s_nop 0
	global_load_dwordx4 v[40:43], v[40:41], off nt
	v_add_co_u32_e32 v44, vcc, s4, v64
	s_mov_b32 s4, 0x2c000
	s_nop 0
	v_addc_co_u32_e32 v45, vcc, 0, v65, vcc
	v_add_co_u32_e32 v48, vcc, s4, v64
	s_mov_b32 s4, 0x30000
	s_nop 0
	v_addc_co_u32_e32 v49, vcc, 0, v65, vcc
	global_load_dwordx4 v[44:47], v[44:45], off nt
	s_nop 0
	global_load_dwordx4 v[48:51], v[48:49], off nt
	v_add_co_u32_e32 v52, vcc, s4, v64
	s_mov_b32 s4, 0x34000
	s_nop 0
	v_addc_co_u32_e32 v53, vcc, 0, v65, vcc
	global_load_dwordx4 v[52:55], v[52:53], off nt
	v_add_co_u32_e32 v56, vcc, s4, v64
	s_mov_b32 s4, 0x38000
	s_nop 0
	v_addc_co_u32_e32 v57, vcc, 0, v65, vcc
	global_load_dwordx4 v[56:59], v[56:57], off nt
	v_add_co_u32_e32 v60, vcc, s4, v64
	s_mov_b32 s4, 0x3c000
	s_nop 0
	v_addc_co_u32_e32 v61, vcc, 0, v65, vcc
	global_load_dwordx4 v[60:63], v[60:61], off nt
	v_add_co_u32_e32 v64, vcc, s4, v64
	s_nop 1
	v_addc_co_u32_e32 v65, vcc, 0, v65, vcc
	global_load_dwordx4 v[88:91], v[64:65], off nt
	s_waitcnt vmcnt(15)
	ds_write2_b32 v73, v4, v5 offset1:1
	ds_write2_b32 v73, v6, v7 offset0:2 offset1:3
	s_waitcnt vmcnt(14)
	ds_write2_b32 v0, v8, v9 offset1:1
	v_add_u32_e32 v0, 0x418, v73
	ds_write2_b32 v0, v10, v11 offset1:1
	v_add_u32_e32 v0, 0x820, v73
	s_waitcnt vmcnt(13)
	ds_write2_b32 v0, v12, v13 offset1:1
	v_add_u32_e32 v0, 0x828, v73
	ds_write2_b32 v0, v14, v15 offset1:1
	v_add_u32_e32 v0, 0xc30, v73
	s_waitcnt vmcnt(12)
	ds_write2_b32 v0, v16, v17 offset1:1
	v_add_u32_e32 v0, 0xc38, v73
	ds_write2_b32 v0, v18, v19 offset1:1
	v_add_u32_e32 v0, 0x1040, v73
	s_waitcnt vmcnt(11)
	ds_write2_b32 v0, v20, v21 offset1:1
	v_add_u32_e32 v0, 0x1048, v73
	ds_write2_b32 v0, v22, v23 offset1:1
	v_add_u32_e32 v0, 0x1450, v73
	s_waitcnt vmcnt(10)
	ds_write2_b32 v0, v24, v25 offset1:1
	v_add_u32_e32 v0, 0x1458, v73
	ds_write2_b32 v0, v26, v27 offset1:1
	v_add_u32_e32 v0, 0x1860, v73
	s_waitcnt vmcnt(9)
	ds_write2_b32 v0, v28, v29 offset1:1
	v_add_u32_e32 v0, 0x1868, v73
	ds_write2_b32 v0, v30, v31 offset1:1
	v_add_u32_e32 v0, 0x1c70, v73
	s_waitcnt vmcnt(8)
	ds_write2_b32 v0, v32, v33 offset1:1
	v_add_u32_e32 v0, 0x1c78, v73
	ds_write2_b32 v0, v34, v35 offset1:1
	v_add_u32_e32 v0, 0x2080, v73
	s_waitcnt vmcnt(7)
	ds_write2_b32 v0, v36, v37 offset1:1
	v_add_u32_e32 v0, 0x2088, v73
	ds_write2_b32 v0, v38, v39 offset1:1
	v_add_u32_e32 v0, 0x2490, v73
	s_waitcnt vmcnt(6)
	ds_write2_b32 v0, v40, v41 offset1:1
	v_add_u32_e32 v0, 0x2498, v73
	ds_write2_b32 v0, v42, v43 offset1:1
	v_add_u32_e32 v0, 0x28a0, v73
	s_waitcnt vmcnt(5)
	ds_write2_b32 v0, v44, v45 offset1:1
	v_add_u32_e32 v0, 0x28a8, v73
	ds_write2_b32 v0, v46, v47 offset1:1
	v_add_u32_e32 v0, 0x2cb0, v73
	s_waitcnt vmcnt(4)
	ds_write2_b32 v0, v48, v49 offset1:1
	v_add_u32_e32 v0, 0x2cb8, v73
	ds_write2_b32 v0, v50, v51 offset1:1
	v_add_u32_e32 v0, 0x30c0, v73
	s_waitcnt vmcnt(3)
	ds_write2_b32 v0, v52, v53 offset1:1
	v_add_u32_e32 v0, 0x30c8, v73
	ds_write2_b32 v0, v54, v55 offset1:1
	v_add_u32_e32 v0, 0x34d0, v73
	s_waitcnt vmcnt(2)
	ds_write2_b32 v0, v56, v57 offset1:1
	v_add_u32_e32 v0, 0x34d8, v73
	ds_write2_b32 v0, v58, v59 offset1:1
	v_add_u32_e32 v0, 0x38e0, v73
	s_waitcnt vmcnt(1)
; DI unsigned cvt_pk_bf16(float lo, float hi) { unsigned r; asm volatile("v_cvt_pk_bf16_f32 %0, %1, %2" : "=v"(r) : "v"(lo), "v"(hi)); return r; }
; #define LDS_WAIT() asm volatile("s_waitcnt lgkmcnt(0)" ::: "memory")
; DI void tr_item(const float* W, int N, const float* scale, bf16_t* WT, int ldk, int koff, int gu, int which, float* scr, int item, int lane) {
;     ...
;     LDS_WAIT();
;     const int c = lane & 7;
; #pragma unroll
;     for (int j = 0; j < 8; ++j) { const int n = (lane >> 3) + 8 * j; const float* s = scr + (8 * c) * 65 + n;
;         u32x4 o; o.x = cvt_pk_bf16(s[0 * 65], s[1 * 65]); o.y = cvt_pk_bf16(s[2 * 65], s[3 * 65]); o.z = cvt_pk_bf16(s[4 * 65], s[5 * 65]); o.w = cvt_pk_bf16(s[6 * 65], s[7 * 65]);
;         const int nn = n0 + n; const int drow = gu ? (((nn >> 7) << 8) + which * 128 + (nn & 127)) : nn;
;         *(u32x4*)(WT + (size_t)drow * ldk + koff + k0 + 8 * c) = o; }
;     LDS_WAIT();
	ds_write2_b32 v0, v60, v61 offset1:1
	v_add_u32_e32 v0, 0x38e8, v73
	ds_write2_b32 v0, v62, v63 offset1:1
	v_add_u32_e32 v0, 0x3cf0, v73
	s_waitcnt vmcnt(0)
	ds_write2_b32 v0, v88, v89 offset1:1
	v_add_u32_e32 v0, 0x3cf8, v73
	ds_write2_b32 v0, v90, v91 offset1:1
	s_waitcnt lgkmcnt(0)
	ds_read2_b32 v[4:5], v93 offset1:65
	s_waitcnt lgkmcnt(0)
	v_cvt_pk_bf16_f32 v4, v4, v5
	ds_read2_b32 v[6:7], v93 offset0:130 offset1:195
	s_waitcnt lgkmcnt(0)
	v_cvt_pk_bf16_f32 v5, v6, v7
	ds_read2_b32 v[6:7], v3 offset0:4 offset1:69
	s_waitcnt lgkmcnt(0)
	v_cvt_pk_bf16_f32 v6, v6, v7
	ds_read2_b32 v[8:9], v3 offset0:134 offset1:199
	s_waitcnt lgkmcnt(0)
	v_cvt_pk_bf16_f32 v7, v8, v9
	v_add3_u32 v8, v2, v156, s75
	v_lshlrev_b32_e32 v0, 7, v158
	v_ashrrev_i32_e32 v9, 31, v8
	v_lshl_add_u64 v[10:11], v[86:87], 0, v[0:1]
	v_lshlrev_b64 v[8:9], 11, v[8:9]
	v_lshl_add_u64 v[8:9], v[10:11], 0, v[8:9]
	ds_read2_b32 v[12:13], v93 offset0:8 offset1:73
	global_store_dwordx4 v[8:9], v[4:7], off
	s_waitcnt lgkmcnt(0)
	s_nop 0
	v_cvt_pk_bf16_f32 v4, v12, v13
	ds_read2_b32 v[6:7], v93 offset0:138 offset1:203
	s_waitcnt lgkmcnt(0)
	v_cvt_pk_bf16_f32 v5, v6, v7
	ds_read2_b32 v[6:7], v3 offset0:12 offset1:77
	s_waitcnt lgkmcnt(0)
	v_cvt_pk_bf16_f32 v6, v6, v7
	ds_read2_b32 v[8:9], v3 offset0:142 offset1:207
	s_waitcnt lgkmcnt(0)
	v_cvt_pk_bf16_f32 v7, v8, v9
	v_add3_u32 v8, v2, v155, s75
	v_ashrrev_i32_e32 v9, 31, v8
	v_lshlrev_b64 v[8:9], 11, v[8:9]
	v_lshl_add_u64 v[8:9], v[10:11], 0, v[8:9]
	ds_read2_b32 v[12:13], v93 offset0:16 offset1:81
	global_store_dwordx4 v[8:9], v[4:7], off
	s_waitcnt lgkmcnt(0)
	s_nop 0
	v_cvt_pk_bf16_f32 v4, v12, v13
	ds_read2_b32 v[6:7], v93 offset0:146 offset1:211
	s_waitcnt lgkmcnt(0)
	v_cvt_pk_bf16_f32 v5, v6, v7
	ds_read2_b32 v[6:7], v3 offset0:20 offset1:85
	s_waitcnt lgkmcnt(0)
	v_cvt_pk_bf16_f32 v6, v6, v7
	ds_read2_b32 v[8:9], v3 offset0:150 offset1:215
	s_waitcnt lgkmcnt(0)
	v_cvt_pk_bf16_f32 v7, v8, v9
	v_add3_u32 v8, v2, v154, s75
	v_ashrrev_i32_e32 v9, 31, v8
	v_lshlrev_b64 v[8:9], 11, v[8:9]
	v_lshl_add_u64 v[8:9], v[10:11], 0, v[8:9]
	ds_read2_b32 v[12:13], v93 offset0:24 offset1:89
	global_store_dwordx4 v[8:9], v[4:7], off
	s_waitcnt lgkmcnt(0)
	s_nop 0
	v_cvt_pk_bf16_f32 v4, v12, v13
	ds_read2_b32 v[6:7], v93 offset0:154 offset1:219
	s_waitcnt lgkmcnt(0)
	v_cvt_pk_bf16_f32 v5, v6, v7
	ds_read2_b32 v[6:7], v3 offset0:28 offset1:93
	s_waitcnt lgkmcnt(0)
	v_cvt_pk_bf16_f32 v6, v6, v7
	ds_read2_b32 v[8:9], v3 offset0:158 offset1:223
	s_waitcnt lgkmcnt(0)
	v_cvt_pk_bf16_f32 v7, v8, v9
	v_add3_u32 v8, v2, v153, s75
	v_ashrrev_i32_e32 v9, 31, v8
	v_lshlrev_b64 v[8:9], 11, v[8:9]
	v_lshl_add_u64 v[8:9], v[10:11], 0, v[8:9]
	ds_read2_b32 v[12:13], v93 offset0:32 offset1:97
	global_store_dwordx4 v[8:9], v[4:7], off
	s_waitcnt lgkmcnt(0)
	s_nop 0
	v_cvt_pk_bf16_f32 v4, v12, v13
	ds_read2_b32 v[6:7], v93 offset0:162 offset1:227
	s_waitcnt lgkmcnt(0)
	v_cvt_pk_bf16_f32 v5, v6, v7
	ds_read2_b32 v[6:7], v3 offset0:36 offset1:101
	s_waitcnt lgkmcnt(0)
	v_cvt_pk_bf16_f32 v6, v6, v7
	ds_read2_b32 v[8:9], v3 offset0:166 offset1:231
	s_waitcnt lgkmcnt(0)
	v_cvt_pk_bf16_f32 v7, v8, v9
	v_add3_u32 v8, v2, v152, s75
	v_ashrrev_i32_e32 v9, 31, v8
	v_lshlrev_b64 v[8:9], 11, v[8:9]
	v_lshl_add_u64 v[8:9], v[10:11], 0, v[8:9]
	ds_read2_b32 v[12:13], v93 offset0:40 offset1:105
	global_store_dwordx4 v[8:9], v[4:7], off
	s_waitcnt lgkmcnt(0)
	s_nop 0
	v_cvt_pk_bf16_f32 v4, v12, v13
	ds_read2_b32 v[6:7], v93 offset0:170 offset1:235
	s_waitcnt lgkmcnt(0)
	v_cvt_pk_bf16_f32 v5, v6, v7
	ds_read2_b32 v[6:7], v3 offset0:44 offset1:109
	s_waitcnt lgkmcnt(0)
	v_cvt_pk_bf16_f32 v6, v6, v7
	ds_read2_b32 v[8:9], v3 offset0:174 offset1:239
	s_waitcnt lgkmcnt(0)
	v_cvt_pk_bf16_f32 v7, v8, v9
	v_add3_u32 v8, v2, v151, s75
	v_ashrrev_i32_e32 v9, 31, v8
	v_lshlrev_b64 v[8:9], 11, v[8:9]
	v_lshl_add_u64 v[8:9], v[10:11], 0, v[8:9]
	ds_read2_b32 v[12:13], v93 offset0:48 offset1:113
	global_store_dwordx4 v[8:9], v[4:7], off
	s_waitcnt lgkmcnt(0)
	s_nop 0
	v_cvt_pk_bf16_f32 v4, v12, v13
	ds_read2_b32 v[6:7], v93 offset0:178 offset1:243
	s_waitcnt lgkmcnt(0)
	v_cvt_pk_bf16_f32 v5, v6, v7
	ds_read2_b32 v[6:7], v3 offset0:52 offset1:117
	s_waitcnt lgkmcnt(0)
	v_cvt_pk_bf16_f32 v6, v6, v7
	ds_read2_b32 v[8:9], v3 offset0:182 offset1:247
	s_waitcnt lgkmcnt(0)
	v_cvt_pk_bf16_f32 v7, v8, v9
	v_add3_u32 v8, v2, v150, s75
	v_ashrrev_i32_e32 v9, 31, v8
	v_lshlrev_b64 v[8:9], 11, v[8:9]
	v_lshl_add_u64 v[8:9], v[10:11], 0, v[8:9]
	ds_read2_b32 v[12:13], v93 offset0:56 offset1:121
	global_store_dwordx4 v[8:9], v[4:7], off
	v_add3_u32 v2, v2, v149, s75
	s_waitcnt lgkmcnt(0)
	v_cvt_pk_bf16_f32 v4, v12, v13
	ds_read2_b32 v[6:7], v93 offset0:186 offset1:251
	s_waitcnt lgkmcnt(0)
	v_cvt_pk_bf16_f32 v5, v6, v7
	ds_read2_b32 v[6:7], v3 offset0:60 offset1:125
	s_waitcnt lgkmcnt(0)
	v_cvt_pk_bf16_f32 v6, v6, v7
	ds_read2_b32 v[8:9], v3 offset0:190 offset1:255
	v_ashrrev_i32_e32 v3, 31, v2
	v_lshlrev_b64 v[2:3], 11, v[2:3]
	v_lshl_add_u64 v[2:3], v[10:11], 0, v[2:3]
	s_waitcnt lgkmcnt(0)
	v_cvt_pk_bf16_f32 v7, v8, v9
	global_store_dwordx4 v[2:3], v[4:7], off
	s_waitcnt lgkmcnt(0)

; DI void tr_item(const float* W, int N, const float* scale, bf16_t* WT, int ldk, int koff, int gu, int which, float* scr, int item, int lane) {
;     const int nblk = N >> 6, kb = item / nblk, nb = item - kb * nblk, k0 = 64 * kb, n0 = 64 * nb;
;     const int lr = lane >> 4, lc = (lane & 15) * 4;
;     f32x4 v[16];
; #pragma unroll
;     for (int i = 0; i < 16; ++i) v[i] = *(const f32x4*)(W + (size_t)(k0 + 4 * i + lr) * N + n0 + lc);
; #pragma unroll
;     for (int i = 0; i < 16; ++i) { const int kk = 4 * i + lr; const float sc = scale ? scale[k0 + kk] : 1.f; float* d = scr + kk * 65 + lc;
;         d[0] = v[i].x * sc; d[1] = v[i].y * sc; d[2] = v[i].z * sc; d[3] = v[i].w * sc; }
; DI void conv_phase(PP P, int l, unsigned char* lds, int G, int cid) {
;     ...
;         if (r < I1) { tr_item(P->in[2] + (size_t)l * DM * NIN, NIN, n1, (bf16_t*)(ws + WS_WIN), DM, 0, 0, 0, scr, r, lane); continue; } r -= I1;
.LBB0_459:
	s_andn2_saveexec_b64 s[12:13], s[68:69]
	s_cbranch_execz .LBB0_384
	s_load_dwordx2 s[4:5], s[0:1], 0x10
	v_ashrrev_i32_e32 v2, 31, v0
	v_lshrrev_b32_e32 v2, 25, v2
	v_add_u32_e32 v0, v0, v2
	v_ashrrev_i32_e32 v0, 7, v0
	v_lshlrev_b32_e32 v88, 6, v0
	v_lshlrev_b32_e32 v158, 13, v0
	s_waitcnt lgkmcnt(0)
	s_add_u32 s4, s4, s64
	v_sub_u32_e32 v2, v114, v158
	v_or_b32_e32 v90, v88, v70
	s_addc_u32 s5, s5, s65
	v_ashrrev_i32_e32 v3, 31, v2
	v_or_b32_e32 v6, 4, v90
	v_lshl_add_u64 v[2:3], v[2:3], 2, s[4:5]
	v_lshlrev_b32_e32 v0, 2, v72
	v_ashrrev_i32_e32 v91, 31, v90
	v_ashrrev_i32_e32 v7, 31, v6
	v_lshl_add_u64 v[2:3], v[2:3], 0, v[0:1]
	v_lshlrev_b64 v[4:5], 15, v[90:91]
	v_lshlrev_b64 v[6:7], 15, v[6:7]
	v_lshl_add_u64 v[4:5], v[2:3], 0, v[4:5]
	v_lshl_add_u64 v[6:7], v[2:3], 0, v[6:7]
	global_load_dwordx4 v[62:65], v[4:5], off nt
	global_load_dwordx4 v[58:61], v[6:7], off nt
	v_or_b32_e32 v4, 8, v90
	v_or_b32_e32 v6, 12, v90
	v_ashrrev_i32_e32 v5, 31, v4
	v_ashrrev_i32_e32 v7, 31, v6
	v_lshlrev_b64 v[4:5], 15, v[4:5]
	v_lshlrev_b64 v[6:7], 15, v[6:7]
	v_lshl_add_u64 v[4:5], v[2:3], 0, v[4:5]
	v_lshl_add_u64 v[6:7], v[2:3], 0, v[6:7]
	global_load_dwordx4 v[54:57], v[4:5], off nt
	global_load_dwordx4 v[50:53], v[6:7], off nt
	v_or_b32_e32 v4, 16, v90
	v_or_b32_e32 v6, 20, v90
	v_ashrrev_i32_e32 v5, 31, v4
	v_ashrrev_i32_e32 v7, 31, v6
	v_lshlrev_b64 v[4:5], 15, v[4:5]
	v_lshlrev_b64 v[6:7], 15, v[6:7]
	v_lshl_add_u64 v[4:5], v[2:3], 0, v[4:5]
	v_lshl_add_u64 v[6:7], v[2:3], 0, v[6:7]
	global_load_dwordx4 v[46:49], v[4:5], off nt
	global_load_dwordx4 v[42:45], v[6:7], off nt
	v_or_b32_e32 v4, 24, v90
	v_or_b32_e32 v6, 28, v90
	v_ashrrev_i32_e32 v5, 31, v4
	v_ashrrev_i32_e32 v7, 31, v6
	v_lshlrev_b64 v[4:5], 15, v[4:5]
	v_lshlrev_b64 v[6:7], 15, v[6:7]
	v_lshl_add_u64 v[4:5], v[2:3], 0, v[4:5]
	v_lshl_add_u64 v[6:7], v[2:3], 0, v[6:7]
	global_load_dwordx4 v[38:41], v[4:5], off nt
	global_load_dwordx4 v[34:37], v[6:7], off nt
	v_or_b32_e32 v4, 32, v90
	v_or_b32_e32 v6, 36, v90
	v_ashrrev_i32_e32 v5, 31, v4
	v_ashrrev_i32_e32 v7, 31, v6
	v_lshlrev_b64 v[4:5], 15, v[4:5]
	v_lshlrev_b64 v[6:7], 15, v[6:7]
	v_lshl_add_u64 v[4:5], v[2:3], 0, v[4:5]
	v_lshl_add_u64 v[6:7], v[2:3], 0, v[6:7]
	global_load_dwordx4 v[30:33], v[4:5], off nt
	global_load_dwordx4 v[26:29], v[6:7], off nt
	v_or_b32_e32 v4, 40, v90
	v_or_b32_e32 v6, 44, v90
	v_ashrrev_i32_e32 v5, 31, v4
	v_ashrrev_i32_e32 v7, 31, v6
	v_lshlrev_b64 v[4:5], 15, v[4:5]
	v_lshlrev_b64 v[6:7], 15, v[6:7]
	v_lshl_add_u64 v[4:5], v[2:3], 0, v[4:5]
	v_lshl_add_u64 v[6:7], v[2:3], 0, v[6:7]
	global_load_dwordx4 v[22:25], v[4:5], off nt
	global_load_dwordx4 v[18:21], v[6:7], off nt
	v_or_b32_e32 v4, 48, v90
	v_or_b32_e32 v6, 52, v90
	v_ashrrev_i32_e32 v5, 31, v4
	v_ashrrev_i32_e32 v7, 31, v6
	v_lshlrev_b64 v[4:5], 15, v[4:5]
	v_lshlrev_b64 v[6:7], 15, v[6:7]
	v_lshl_add_u64 v[4:5], v[2:3], 0, v[4:5]
	v_lshl_add_u64 v[6:7], v[2:3], 0, v[6:7]
	global_load_dwordx4 v[14:17], v[4:5], off nt
	global_load_dwordx4 v[10:13], v[6:7], off nt
	v_or_b32_e32 v4, 56, v90
	v_or_b32_e32 v6, 60, v90
	v_ashrrev_i32_e32 v5, 31, v4
	v_ashrrev_i32_e32 v7, 31, v6
	v_lshlrev_b64 v[4:5], 15, v[4:5]
	v_lshlrev_b64 v[6:7], 15, v[6:7]
	v_lshl_add_u64 v[4:5], v[2:3], 0, v[4:5]
	v_lshl_add_u64 v[2:3], v[2:3], 0, v[6:7]
	global_load_dwordx4 v[6:9], v[4:5], off nt
	s_nop 0
	global_load_dwordx4 v[2:5], v[2:3], off nt
	v_cndmask_b32_e64 v0, 0, 1, s[66:67]
	v_cmp_ne_u32_e64 s[40:41], 1, v0
	s_andn2_b64 vcc, exec, s[66:67]
	v_ashrrev_i32_e32 v89, 31, v88
	s_cbranch_vccnz .LBB0_483
	v_lshl_add_u64 v[90:91], v[90:91], 2, s[46:47]
	global_load_dword v0, v[90:91], off
	s_waitcnt vmcnt(0)
	v_pk_mul_f32 v[90:91], v[62:63], v[0:1] op_sel_hi:[1,0]
	ds_write2_b32 v73, v90, v91 offset1:1
	v_pk_mul_f32 v[90:91], v[64:65], v[0:1] op_sel_hi:[1,0]
	ds_write2_b32 v73, v90, v91 offset0:2 offset1:3
	v_lshl_add_u64 v[90:91], v[88:89], 0, v[70:71]
	v_lshl_add_u64 v[90:91], v[90:91], 2, s[46:47]
	global_load_dword v0, v[90:91], off offset:16
	s_cbranch_execnz .LBB0_463
